# peer_out phase hand-rewritten the same way (rolling gather pipeline, ids and coefficients staged via LDS, permlane swaps for the cross-group reduction)
# speedup vs baseline: 1.0294x; 1.0294x over previous
; __device__ __forceinline__ unsigned xb_ld(unsigned* p)              { return __hip_atomic_load(p, __ATOMIC_RELAXED, __HIP_MEMORY_SCOPE_AGENT); }
; __device__ __forceinline__ unsigned xb_add(unsigned* p, unsigned v) { return __hip_atomic_fetch_add(p, v, __ATOMIC_RELAXED, __HIP_MEMORY_SCOPE_AGENT); }
; __device__ __forceinline__ void xcd_barrier_complete(unsigned* bar, unsigned x, unsigned& nloc, unsigned& nx) {
;     const unsigned G = gridDim.x * gridDim.y * gridDim.z;
;     unsigned sum, cnt, mine, sp = 0u;
;     for (;;) {
;         sum = 0u; cnt = 0u; mine = 0u;
; #pragma unroll
;         for (unsigned j = 0; j < 16; ++j) { const unsigned c = xb_ld(&bar[XB_XCNT(j)]); sum += c; cnt += (c > 0u) ? 1u : 0u; mine = (j == x) ? c : mine; }
; __device__ __forceinline__ void xcd_barrier(const XcdBarrier& b) {
;     asm volatile("s_waitcnt vmcnt(0)" ::: "memory");
;     __syncthreads();
;     if (threadIdx.x == 0) {
;         unsigned* bar = b.bar;
;         __builtin_amdgcn_s_waitcnt(0);
;         unsigned nloc = b.st[0], nx = b.st[1];
;         if (nloc == 0u) { xcd_barrier_complete(bar, b.x, nloc, nx); b.st[0] = nloc; b.st[1] = nx; }
;         const unsigned old = xb_add(&bar[XB_XSUB(b.x)], 1u);
;         const unsigned gen = old / nloc;
;         if (old + 1u == (gen + 1u) * nloc) {
.LBB0_923:
.Lseam_ph10:
	s_cmp_gt_i32 s93, 11
	s_cselect_b64 s[4:5], -1, 0
	s_cmp_lg_u32 s94, 0
	s_cselect_b64 s[6:7], -1, 0
	s_and_b64 s[4:5], s[4:5], s[6:7]
	s_andn2_b64 vcc, exec, s[4:5]
	s_cbranch_vccnz .LBB0_973
	s_waitcnt vmcnt(0)
	s_waitcnt vmcnt(0)
	s_barrier
	s_and_saveexec_b64 s[4:5], s[90:91]
	s_cbranch_execz .LBB0_972
	s_add_i32 s1, 0, 0x20080
	v_mov_b32_e32 v0, s1
	s_waitcnt vmcnt(0) expcnt(0) lgkmcnt(0)
	ds_read_b32 v2, v0
	s_add_i32 s1, 0, 0x20084
	v_mov_b32_e32 v0, s1
	ds_read_b32 v0, v0
	s_waitcnt lgkmcnt(1)
	v_cmp_ne_u32_e32 vcc, 0, v2
	s_cbranch_vccnz .LBB0_940
	s_load_dwordx2 s[10:11], s[22:23], 0x4
	s_add_u32 s6, s86, 0x1000
	s_addc_u32 s7, s87, 0
	s_add_u32 s8, s86, 0x1100
	s_addc_u32 s9, s87, 0
	s_waitcnt lgkmcnt(0)
	s_mul_i32 s0, s10, s0
	s_add_u32 s10, s86, 0x1200
	s_mul_i32 s0, s0, s11
	s_addc_u32 s11, s87, 0
	s_add_u32 s12, s86, 0x1300
	s_addc_u32 s13, s87, 0
	s_mov_b32 s1, 1
	v_mov_b32_e32 v16, 0
	s_branch .LBB0_928

; __device__ __forceinline__ void phase_peer_out(const Params& P, int l) {
;     const int lane = threadIdx.x & 63, sub = lane & 7, grp = lane >> 3;
;     const int s = blockIdx.x & 7, nslots = (gridDim.x >> 3) * 8, wslot = (blockIdx.x >> 3) * 8 + (threadIdx.x >> 6);
;     const unsigned char* PV = P.ws + WS_PT + (size_t)(2 * l + 1) * NEXP * DM + (size_t)s * NEXP * 128;
;     const unsigned lo = 16u * (unsigned)sub;
;     const int* eidx = (const int*)(P.ws + WS_R5) + grp; const float* cfp = (const float*)(P.ws + WS_CF) + grp;
;     if ((int)(blockIdx.x >> 3) * 8 >= nslots) return;
;     int en[16];
; #pragma unroll
;     for (int i = 0; i < 16; ++i) en[i] = eidx[(size_t)wslot * 128 + 8 * i];
;     for (int t = wslot; t < T; t += nslots) {
;         u32x4 vq[16]; float cf[16];
; #pragma unroll
;         for (int i = 0; i < 16; ++i) { vq[i] = *(const u32x4*)(PV + ((unsigned)en[i] * 128u + lo)); cf[i] = cfp[(size_t)t * 128 + 8 * i]; }
;         float* yp = P.out + (size_t)t * DM + 128 * s + 16 * sub + ((lane & 16) ? 8 : 0) + ((lane & 32) ? 4 : 0);
;         const f32x4 xo = *(const f32x4*)yp;
;         { const int tn = (t + nslots < T) ? t + nslots : t;
; #pragma unroll
;           for (int i = 0; i < 16; ++i) en[i] = eidx[(size_t)tn * 128 + 8 * i]; }
.LBB0_1027:
	s_cmp_lt_i32 s92, 13
	s_cselect_b64 s[0:1], -1, 0
	s_cmp_gt_i32 s93, 12
	s_cselect_b64 s[4:5], -1, 0
	s_and_b64 s[0:1], s[0:1], s[4:5]
	s_andn2_b64 vcc, exec, s[0:1]
	s_cbranch_vccnz .LBB0_1083
	s_load_dword s0, s[96:97], 0xd0
	s_waitcnt lgkmcnt(0)
	s_cmpk_lg_u32 s0, 0x100
	s_cbranch_scc1 .Lpout_orig_L0
	s_mov_b64 exec, -1
	v_and_b32_e32 v234, 63, v160
	v_and_b32_e32 v226, 7, v160
	v_bfe_u32 v235, v160, 3, 3
	v_lshrrev_b32_e32 v230, 6, v160
	v_lshlrev_b32_e32 v227, 3, v234
	v_readfirstlane_b32 s0, v230
	v_lshlrev_b32_e32 v230, 10, v230
	v_lshl_add_u32 v233, v235, 6, v230
	v_and_b32_e32 v231, 3, v234
	v_lshl_add_u32 v232, v231, 7, v230
	v_lshrrev_b32_e32 v231, 2, v234
	v_lshl_add_u32 v232, v231, 2, v232
	v_bfe_u32 v230, v234, 4, 1
	v_lshrrev_b32_e32 v231, 5, v234
	v_lshlrev_b32_e32 v228, 5, v226
	v_lshl_add_u32 v228, v230, 4, v228
	v_lshl_add_u32 v228, v231, 3, v228
	v_lshlrev_b32_e32 v229, 1, v228
	v_lshlrev_b32_e32 v226, 4, v226
	s_nop 3
	s_and_b32 s1, s2, 7
	s_and_b32 s3, s2, -8
	s_add_u32 s3, s3, s0
	s_lshl_b32 s28, s1, 21
	s_add_u32 s20, s86, s28
	s_addc_u32 s21, s87, 0
	s_add_u32 s20, s20, 0x1d000000
	s_addc_u32 s21, s21, 0
	s_lshl_b32 s28, s3, 9
	s_add_u32 s22, s86, s28
	s_addc_u32 s23, s87, 0
	s_add_u32 s24, s22, 0x10000000
	s_addc_u32 s25, s23, 0
	s_add_u32 s22, s22, 0x18000000
	s_addc_u32 s23, s23, 0
	s_lshl_b32 s28, s3, 12
	s_lshl_b32 s29, s1, 9
	s_add_u32 s28, s28, s29
	s_add_u32 s4, s84, s28
	s_addc_u32 s5, s85, 0
	s_lshr_b32 s28, s28, 1
	s_add_u32 s6, s86, s28
	s_addc_u32 s7, s87, 0
	s_add_u32 s6, s6, 0x4000000
	s_addc_u32 s7, s7, 0
	s_mov_b32 s8, 0xff00ff
	s_mov_b32 s9, 0xff00ff
	s_mov_b32 s10, 0x3fb504f3
	s_mov_b32 s30, s22
	s_mov_b32 s31, s23
	global_load_dwordx2 v[218:219], v227, s[30:31]
	s_waitcnt vmcnt(0)
	ds_write2_b32 v232, v218, v219 offset1:16
	ds_read_b128 v[128:131], v233
	ds_read_b128 v[132:135], v233 offset:16
	ds_read_b128 v[136:139], v233 offset:32
	ds_read_b128 v[140:143], v233 offset:48
	s_waitcnt lgkmcnt(0)
	v_lshl_add_u32 v230, v128, 7, v226
	global_load_dwordx4 v[0:3], v230, s[20:21]
	v_lshl_add_u32 v231, v129, 7, v226
	global_load_dwordx4 v[4:7], v231, s[20:21]
	v_lshl_add_u32 v230, v130, 7, v226
	global_load_dwordx4 v[8:11], v230, s[20:21]
	v_lshl_add_u32 v231, v131, 7, v226
	global_load_dwordx4 v[12:15], v231, s[20:21]
	v_lshl_add_u32 v230, v132, 7, v226
	global_load_dwordx4 v[16:19], v230, s[20:21]
	v_lshl_add_u32 v231, v133, 7, v226
	global_load_dwordx4 v[20:23], v231, s[20:21]
	v_lshl_add_u32 v230, v134, 7, v226
	global_load_dwordx4 v[24:27], v230, s[20:21]
	v_lshl_add_u32 v231, v135, 7, v226
	global_load_dwordx4 v[28:31], v231, s[20:21]
	v_lshl_add_u32 v230, v136, 7, v226
	global_load_dwordx4 v[32:35], v230, s[20:21]
	v_lshl_add_u32 v231, v137, 7, v226
	global_load_dwordx4 v[36:39], v231, s[20:21]
	v_lshl_add_u32 v230, v138, 7, v226
	global_load_dwordx4 v[40:43], v230, s[20:21]
	v_lshl_add_u32 v231, v139, 7, v226
	global_load_dwordx4 v[44:47], v231, s[20:21]
	v_lshl_add_u32 v230, v140, 7, v226
	global_load_dwordx4 v[48:51], v230, s[20:21]
	v_lshl_add_u32 v231, v141, 7, v226
	global_load_dwordx4 v[52:55], v231, s[20:21]
	v_lshl_add_u32 v230, v142, 7, v226
	global_load_dwordx4 v[56:59], v230, s[20:21]
	v_lshl_add_u32 v231, v143, 7, v226
	global_load_dwordx4 v[60:63], v231, s[20:21]
	s_add_u32 s30, s22, 0x20000
	s_addc_u32 s31, s23, 0
	global_load_dwordx2 v[218:219], v227, s[30:31]
	s_waitcnt vmcnt(0)
	ds_write2_b32 v232, v218, v219 offset1:16
	ds_read_b128 v[128:131], v233
	ds_read_b128 v[132:135], v233 offset:16
	ds_read_b128 v[136:139], v233 offset:32
	ds_read_b128 v[140:143], v233 offset:48
	s_waitcnt lgkmcnt(0)
	v_lshl_add_u32 v230, v128, 7, v226
	global_load_dwordx4 v[64:67], v230, s[20:21]
	v_lshl_add_u32 v231, v129, 7, v226
	global_load_dwordx4 v[68:71], v231, s[20:21]
	v_lshl_add_u32 v230, v130, 7, v226
	global_load_dwordx4 v[72:75], v230, s[20:21]
	v_lshl_add_u32 v231, v131, 7, v226
	global_load_dwordx4 v[76:79], v231, s[20:21]
	v_lshl_add_u32 v230, v132, 7, v226
	global_load_dwordx4 v[80:83], v230, s[20:21]
	v_lshl_add_u32 v231, v133, 7, v226
	global_load_dwordx4 v[84:87], v231, s[20:21]
	v_lshl_add_u32 v230, v134, 7, v226
	global_load_dwordx4 v[88:91], v230, s[20:21]
	v_lshl_add_u32 v231, v135, 7, v226
	global_load_dwordx4 v[92:95], v231, s[20:21]
	v_lshl_add_u32 v230, v136, 7, v226
	global_load_dwordx4 v[96:99], v230, s[20:21]
	v_lshl_add_u32 v231, v137, 7, v226
	global_load_dwordx4 v[100:103], v231, s[20:21]
	v_lshl_add_u32 v230, v138, 7, v226
	global_load_dwordx4 v[104:107], v230, s[20:21]
	v_lshl_add_u32 v231, v139, 7, v226
	global_load_dwordx4 v[108:111], v231, s[20:21]
	v_lshl_add_u32 v230, v140, 7, v226
	global_load_dwordx4 v[112:115], v230, s[20:21]
	v_lshl_add_u32 v231, v141, 7, v226
	global_load_dwordx4 v[116:119], v231, s[20:21]
	v_lshl_add_u32 v230, v142, 7, v226
	global_load_dwordx4 v[120:123], v230, s[20:21]
	v_lshl_add_u32 v231, v143, 7, v226
	global_load_dwordx4 v[124:127], v231, s[20:21]
	s_add_u32 s30, s22, 0x40000
	s_addc_u32 s31, s23, 0
	global_load_dwordx2 v[220:221], v227, s[30:31]
	s_mov_b32 s30, s24
	s_mov_b32 s31, s25
	global_load_dwordx2 v[224:225], v227, s[30:31]
	s_mov_b32 s30, s4
	s_mov_b32 s31, s5
	global_load_dwordx4 v[210:213], v229, s[30:31]
	s_waitcnt vmcnt(0)
	s_mov_b32 s28, 0
; __device__ __forceinline__ void phase_peer_out(const Params& P, int l) {
;     ...
;         u32x4 vq[16]; float cf[16];
; #pragma unroll
;         for (int i = 0; i < 16; ++i) { vq[i] = *(const u32x4*)(PV + ((unsigned)en[i] * 128u + lo)); cf[i] = cfp[(size_t)t * 128 + 8 * i]; }
;         float* yp = P.out + (size_t)t * DM + 128 * s + 16 * sub + ((lane & 16) ? 8 : 0) + ((lane & 32) ? 4 : 0);
;         const f32x4 xo = *(const f32x4*)yp;
;         { const int tn = (t + nslots < T) ? t + nslots : t;
; #pragma unroll
;           for (int i = 0; i < 16; ++i) en[i] = eidx[(size_t)tn * 128 + 8 * i]; }
;         __builtin_amdgcn_sched_barrier(0);
;         f32x2 acc2[8];
; #pragma unroll
;         for (int c = 0; c < 8; ++c) acc2[c] = (f32x2){0.f, 0.f};
; #pragma unroll
;         for (int i = 0; i < 16; ++i) { f32x2 vd[8]; fp8x16_dec2(vq[i], vd); const f32x2 c2 = {cf[i], cf[i]};
; #pragma unroll
;             for (int c = 0; c < 8; ++c) acc2[c] = __builtin_elementwise_fma(c2, vd[c], acc2[c]);
;             __builtin_amdgcn_sched_barrier(0); }
.Lpout_loop_L0:
	s_waitcnt vmcnt(17)
	ds_write2_b32 v232, v220, v221 offset1:16
	ds_write2_b32 v232, v224, v225 offset0:128 offset1:144
	s_add_u32 s29, s28, 3
	s_min_u32 s29, s29, 0x7f
	s_lshl_b32 s29, s29, 17
	s_add_u32 s30, s22, s29
	s_addc_u32 s31, s23, 0
	global_load_dwordx2 v[218:219], v227, s[30:31]
	s_add_u32 s29, s28, 1
	s_min_u32 s29, s29, 0x7f
	s_lshl_b32 s29, s29, 17
	s_add_u32 s30, s24, s29
	s_addc_u32 s31, s25, 0
	global_load_dwordx2 v[222:223], v227, s[30:31]
	s_add_u32 s29, s28, 1
	s_min_u32 s29, s29, 0x7f
	s_lshl_b32 s29, s29, 20
	s_add_u32 s30, s4, s29
	s_addc_u32 s31, s5, 0
	global_load_dwordx4 v[214:217], v229, s[30:31]
	ds_read_b128 v[128:131], v233
	ds_read_b128 v[132:135], v233 offset:16
	ds_read_b128 v[136:139], v233 offset:32
	ds_read_b128 v[140:143], v233 offset:48
	ds_read_b128 v[144:147], v233 offset:512
	ds_read_b128 v[148:151], v233 offset:528
	ds_read_b128 v[152:155], v233 offset:544
	ds_read_b128 v[156:159], v233 offset:560
	s_waitcnt lgkmcnt(0)
	v_cvt_pk_f32_fp8_e32 v[162:163], v0
	v_cvt_pk_f32_fp8_sdwa v[164:165], v0 src0_sel:WORD_1
	v_cvt_pk_f32_fp8_e32 v[166:167], v1
	v_cvt_pk_f32_fp8_sdwa v[168:169], v1 src0_sel:WORD_1
	v_cvt_pk_f32_fp8_e32 v[170:171], v2
	v_cvt_pk_f32_fp8_sdwa v[172:173], v2 src0_sel:WORD_1
	v_cvt_pk_f32_fp8_e32 v[174:175], v3
	v_cvt_pk_f32_fp8_sdwa v[176:177], v3 src0_sel:WORD_1
	v_lshl_add_u32 v230, v128, 7, v226
	global_load_dwordx4 v[0:3], v230, s[20:21]
	v_pk_fma_f32 v[194:195], v[144:145], v[162:163], 0 op_sel_hi:[0,1,0]
	v_pk_fma_f32 v[196:197], v[144:145], v[164:165], 0 op_sel_hi:[0,1,0]
	v_pk_fma_f32 v[198:199], v[144:145], v[166:167], 0 op_sel_hi:[0,1,0]
	v_pk_fma_f32 v[200:201], v[144:145], v[168:169], 0 op_sel_hi:[0,1,0]
	v_pk_fma_f32 v[202:203], v[144:145], v[170:171], 0 op_sel_hi:[0,1,0]
	v_pk_fma_f32 v[204:205], v[144:145], v[172:173], 0 op_sel_hi:[0,1,0]
	v_pk_fma_f32 v[206:207], v[144:145], v[174:175], 0 op_sel_hi:[0,1,0]
	v_pk_fma_f32 v[208:209], v[144:145], v[176:177], 0 op_sel_hi:[0,1,0]
	v_cvt_pk_f32_fp8_e32 v[178:179], v4
	v_cvt_pk_f32_fp8_sdwa v[180:181], v4 src0_sel:WORD_1
	v_cvt_pk_f32_fp8_e32 v[182:183], v5
	v_cvt_pk_f32_fp8_sdwa v[184:185], v5 src0_sel:WORD_1
	v_cvt_pk_f32_fp8_e32 v[186:187], v6
	v_cvt_pk_f32_fp8_sdwa v[188:189], v6 src0_sel:WORD_1
	v_cvt_pk_f32_fp8_e32 v[190:191], v7
	v_cvt_pk_f32_fp8_sdwa v[192:193], v7 src0_sel:WORD_1
	v_lshl_add_u32 v231, v129, 7, v226
	global_load_dwordx4 v[4:7], v231, s[20:21]
	v_pk_fma_f32 v[194:195], v[144:145], v[178:179], v[194:195] op_sel:[1,0,0] op_sel_hi:[1,1,1]
	v_pk_fma_f32 v[196:197], v[144:145], v[180:181], v[196:197] op_sel:[1,0,0] op_sel_hi:[1,1,1]
	v_pk_fma_f32 v[198:199], v[144:145], v[182:183], v[198:199] op_sel:[1,0,0] op_sel_hi:[1,1,1]
	v_pk_fma_f32 v[200:201], v[144:145], v[184:185], v[200:201] op_sel:[1,0,0] op_sel_hi:[1,1,1]
	v_pk_fma_f32 v[202:203], v[144:145], v[186:187], v[202:203] op_sel:[1,0,0] op_sel_hi:[1,1,1]
	v_pk_fma_f32 v[204:205], v[144:145], v[188:189], v[204:205] op_sel:[1,0,0] op_sel_hi:[1,1,1]
	v_pk_fma_f32 v[206:207], v[144:145], v[190:191], v[206:207] op_sel:[1,0,0] op_sel_hi:[1,1,1]
	v_pk_fma_f32 v[208:209], v[144:145], v[192:193], v[208:209] op_sel:[1,0,0] op_sel_hi:[1,1,1]
	v_cvt_pk_f32_fp8_e32 v[162:163], v8
	v_cvt_pk_f32_fp8_sdwa v[164:165], v8 src0_sel:WORD_1
	v_cvt_pk_f32_fp8_e32 v[166:167], v9
	v_cvt_pk_f32_fp8_sdwa v[168:169], v9 src0_sel:WORD_1
	v_cvt_pk_f32_fp8_e32 v[170:171], v10
	v_cvt_pk_f32_fp8_sdwa v[172:173], v10 src0_sel:WORD_1
	v_cvt_pk_f32_fp8_e32 v[174:175], v11
	v_cvt_pk_f32_fp8_sdwa v[176:177], v11 src0_sel:WORD_1
	v_lshl_add_u32 v230, v130, 7, v226
	global_load_dwordx4 v[8:11], v230, s[20:21]
	v_pk_fma_f32 v[194:195], v[146:147], v[162:163], v[194:195] op_sel_hi:[0,1,1]
	v_pk_fma_f32 v[196:197], v[146:147], v[164:165], v[196:197] op_sel_hi:[0,1,1]
	v_pk_fma_f32 v[198:199], v[146:147], v[166:167], v[198:199] op_sel_hi:[0,1,1]
	v_pk_fma_f32 v[200:201], v[146:147], v[168:169], v[200:201] op_sel_hi:[0,1,1]
	v_pk_fma_f32 v[202:203], v[146:147], v[170:171], v[202:203] op_sel_hi:[0,1,1]
	v_pk_fma_f32 v[204:205], v[146:147], v[172:173], v[204:205] op_sel_hi:[0,1,1]
	v_pk_fma_f32 v[206:207], v[146:147], v[174:175], v[206:207] op_sel_hi:[0,1,1]
	v_pk_fma_f32 v[208:209], v[146:147], v[176:177], v[208:209] op_sel_hi:[0,1,1]
	v_cvt_pk_f32_fp8_e32 v[178:179], v12
	v_cvt_pk_f32_fp8_sdwa v[180:181], v12 src0_sel:WORD_1
	v_cvt_pk_f32_fp8_e32 v[182:183], v13
	v_cvt_pk_f32_fp8_sdwa v[184:185], v13 src0_sel:WORD_1
	v_cvt_pk_f32_fp8_e32 v[186:187], v14
	v_cvt_pk_f32_fp8_sdwa v[188:189], v14 src0_sel:WORD_1
	v_cvt_pk_f32_fp8_e32 v[190:191], v15
	v_cvt_pk_f32_fp8_sdwa v[192:193], v15 src0_sel:WORD_1
	v_lshl_add_u32 v231, v131, 7, v226
	global_load_dwordx4 v[12:15], v231, s[20:21]
	v_pk_fma_f32 v[194:195], v[146:147], v[178:179], v[194:195] op_sel:[1,0,0] op_sel_hi:[1,1,1]
	v_pk_fma_f32 v[196:197], v[146:147], v[180:181], v[196:197] op_sel:[1,0,0] op_sel_hi:[1,1,1]
	v_pk_fma_f32 v[198:199], v[146:147], v[182:183], v[198:199] op_sel:[1,0,0] op_sel_hi:[1,1,1]
	v_pk_fma_f32 v[200:201], v[146:147], v[184:185], v[200:201] op_sel:[1,0,0] op_sel_hi:[1,1,1]
	v_pk_fma_f32 v[202:203], v[146:147], v[186:187], v[202:203] op_sel:[1,0,0] op_sel_hi:[1,1,1]
	v_pk_fma_f32 v[204:205], v[146:147], v[188:189], v[204:205] op_sel:[1,0,0] op_sel_hi:[1,1,1]
	v_pk_fma_f32 v[206:207], v[146:147], v[190:191], v[206:207] op_sel:[1,0,0] op_sel_hi:[1,1,1]
	v_pk_fma_f32 v[208:209], v[146:147], v[192:193], v[208:209] op_sel:[1,0,0] op_sel_hi:[1,1,1]
	v_cvt_pk_f32_fp8_e32 v[162:163], v16
	v_cvt_pk_f32_fp8_sdwa v[164:165], v16 src0_sel:WORD_1
	v_cvt_pk_f32_fp8_e32 v[166:167], v17
	v_cvt_pk_f32_fp8_sdwa v[168:169], v17 src0_sel:WORD_1
; __device__ __forceinline__ void phase_peer_out(const Params& P, int l) {
;     ...
;         u32x4 vq[16]; float cf[16];
; #pragma unroll
;         for (int i = 0; i < 16; ++i) { vq[i] = *(const u32x4*)(PV + ((unsigned)en[i] * 128u + lo)); cf[i] = cfp[(size_t)t * 128 + 8 * i]; }
;         float* yp = P.out + (size_t)t * DM + 128 * s + 16 * sub + ((lane & 16) ? 8 : 0) + ((lane & 32) ? 4 : 0);
;         const f32x4 xo = *(const f32x4*)yp;
;         { const int tn = (t + nslots < T) ? t + nslots : t;
; #pragma unroll
;           for (int i = 0; i < 16; ++i) en[i] = eidx[(size_t)tn * 128 + 8 * i]; }
;         __builtin_amdgcn_sched_barrier(0);
;         f32x2 acc2[8];
; #pragma unroll
;         for (int c = 0; c < 8; ++c) acc2[c] = (f32x2){0.f, 0.f};
; #pragma unroll
;         for (int i = 0; i < 16; ++i) { f32x2 vd[8]; fp8x16_dec2(vq[i], vd); const f32x2 c2 = {cf[i], cf[i]};
; #pragma unroll
;             for (int c = 0; c < 8; ++c) acc2[c] = __builtin_elementwise_fma(c2, vd[c], acc2[c]);
;             __builtin_amdgcn_sched_barrier(0); }
	v_cvt_pk_f32_fp8_e32 v[170:171], v18
	v_cvt_pk_f32_fp8_sdwa v[172:173], v18 src0_sel:WORD_1
	v_cvt_pk_f32_fp8_e32 v[174:175], v19
	v_cvt_pk_f32_fp8_sdwa v[176:177], v19 src0_sel:WORD_1
	v_lshl_add_u32 v230, v132, 7, v226
	global_load_dwordx4 v[16:19], v230, s[20:21]
	v_pk_fma_f32 v[194:195], v[148:149], v[162:163], v[194:195] op_sel_hi:[0,1,1]
	v_pk_fma_f32 v[196:197], v[148:149], v[164:165], v[196:197] op_sel_hi:[0,1,1]
	v_pk_fma_f32 v[198:199], v[148:149], v[166:167], v[198:199] op_sel_hi:[0,1,1]
	v_pk_fma_f32 v[200:201], v[148:149], v[168:169], v[200:201] op_sel_hi:[0,1,1]
	v_pk_fma_f32 v[202:203], v[148:149], v[170:171], v[202:203] op_sel_hi:[0,1,1]
	v_pk_fma_f32 v[204:205], v[148:149], v[172:173], v[204:205] op_sel_hi:[0,1,1]
	v_pk_fma_f32 v[206:207], v[148:149], v[174:175], v[206:207] op_sel_hi:[0,1,1]
	v_pk_fma_f32 v[208:209], v[148:149], v[176:177], v[208:209] op_sel_hi:[0,1,1]
	v_cvt_pk_f32_fp8_e32 v[178:179], v20
	v_cvt_pk_f32_fp8_sdwa v[180:181], v20 src0_sel:WORD_1
	v_cvt_pk_f32_fp8_e32 v[182:183], v21
	v_cvt_pk_f32_fp8_sdwa v[184:185], v21 src0_sel:WORD_1
	v_cvt_pk_f32_fp8_e32 v[186:187], v22
	v_cvt_pk_f32_fp8_sdwa v[188:189], v22 src0_sel:WORD_1
	v_cvt_pk_f32_fp8_e32 v[190:191], v23
	v_cvt_pk_f32_fp8_sdwa v[192:193], v23 src0_sel:WORD_1
	v_lshl_add_u32 v231, v133, 7, v226
	global_load_dwordx4 v[20:23], v231, s[20:21]
	v_pk_fma_f32 v[194:195], v[148:149], v[178:179], v[194:195] op_sel:[1,0,0] op_sel_hi:[1,1,1]
	v_pk_fma_f32 v[196:197], v[148:149], v[180:181], v[196:197] op_sel:[1,0,0] op_sel_hi:[1,1,1]
	v_pk_fma_f32 v[198:199], v[148:149], v[182:183], v[198:199] op_sel:[1,0,0] op_sel_hi:[1,1,1]
	v_pk_fma_f32 v[200:201], v[148:149], v[184:185], v[200:201] op_sel:[1,0,0] op_sel_hi:[1,1,1]
	v_pk_fma_f32 v[202:203], v[148:149], v[186:187], v[202:203] op_sel:[1,0,0] op_sel_hi:[1,1,1]
	v_pk_fma_f32 v[204:205], v[148:149], v[188:189], v[204:205] op_sel:[1,0,0] op_sel_hi:[1,1,1]
	v_pk_fma_f32 v[206:207], v[148:149], v[190:191], v[206:207] op_sel:[1,0,0] op_sel_hi:[1,1,1]
	v_pk_fma_f32 v[208:209], v[148:149], v[192:193], v[208:209] op_sel:[1,0,0] op_sel_hi:[1,1,1]
	v_cvt_pk_f32_fp8_e32 v[162:163], v24
	v_cvt_pk_f32_fp8_sdwa v[164:165], v24 src0_sel:WORD_1
	v_cvt_pk_f32_fp8_e32 v[166:167], v25
	v_cvt_pk_f32_fp8_sdwa v[168:169], v25 src0_sel:WORD_1
	v_cvt_pk_f32_fp8_e32 v[170:171], v26
	v_cvt_pk_f32_fp8_sdwa v[172:173], v26 src0_sel:WORD_1
	v_cvt_pk_f32_fp8_e32 v[174:175], v27
	v_cvt_pk_f32_fp8_sdwa v[176:177], v27 src0_sel:WORD_1
	v_lshl_add_u32 v230, v134, 7, v226
	global_load_dwordx4 v[24:27], v230, s[20:21]
	v_pk_fma_f32 v[194:195], v[150:151], v[162:163], v[194:195] op_sel_hi:[0,1,1]
	v_pk_fma_f32 v[196:197], v[150:151], v[164:165], v[196:197] op_sel_hi:[0,1,1]
	v_pk_fma_f32 v[198:199], v[150:151], v[166:167], v[198:199] op_sel_hi:[0,1,1]
	v_pk_fma_f32 v[200:201], v[150:151], v[168:169], v[200:201] op_sel_hi:[0,1,1]
	v_pk_fma_f32 v[202:203], v[150:151], v[170:171], v[202:203] op_sel_hi:[0,1,1]
	v_pk_fma_f32 v[204:205], v[150:151], v[172:173], v[204:205] op_sel_hi:[0,1,1]
	v_pk_fma_f32 v[206:207], v[150:151], v[174:175], v[206:207] op_sel_hi:[0,1,1]
	v_pk_fma_f32 v[208:209], v[150:151], v[176:177], v[208:209] op_sel_hi:[0,1,1]
	v_cvt_pk_f32_fp8_e32 v[178:179], v28
	v_cvt_pk_f32_fp8_sdwa v[180:181], v28 src0_sel:WORD_1
	v_cvt_pk_f32_fp8_e32 v[182:183], v29
	v_cvt_pk_f32_fp8_sdwa v[184:185], v29 src0_sel:WORD_1
	v_cvt_pk_f32_fp8_e32 v[186:187], v30
	v_cvt_pk_f32_fp8_sdwa v[188:189], v30 src0_sel:WORD_1
	v_cvt_pk_f32_fp8_e32 v[190:191], v31
	v_cvt_pk_f32_fp8_sdwa v[192:193], v31 src0_sel:WORD_1
	v_lshl_add_u32 v231, v135, 7, v226
	global_load_dwordx4 v[28:31], v231, s[20:21]
	v_pk_fma_f32 v[194:195], v[150:151], v[178:179], v[194:195] op_sel:[1,0,0] op_sel_hi:[1,1,1]
	v_pk_fma_f32 v[196:197], v[150:151], v[180:181], v[196:197] op_sel:[1,0,0] op_sel_hi:[1,1,1]
	v_pk_fma_f32 v[198:199], v[150:151], v[182:183], v[198:199] op_sel:[1,0,0] op_sel_hi:[1,1,1]
	v_pk_fma_f32 v[200:201], v[150:151], v[184:185], v[200:201] op_sel:[1,0,0] op_sel_hi:[1,1,1]
	v_pk_fma_f32 v[202:203], v[150:151], v[186:187], v[202:203] op_sel:[1,0,0] op_sel_hi:[1,1,1]
	v_pk_fma_f32 v[204:205], v[150:151], v[188:189], v[204:205] op_sel:[1,0,0] op_sel_hi:[1,1,1]
	v_pk_fma_f32 v[206:207], v[150:151], v[190:191], v[206:207] op_sel:[1,0,0] op_sel_hi:[1,1,1]
	v_pk_fma_f32 v[208:209], v[150:151], v[192:193], v[208:209] op_sel:[1,0,0] op_sel_hi:[1,1,1]
	v_cvt_pk_f32_fp8_e32 v[162:163], v32
	v_cvt_pk_f32_fp8_sdwa v[164:165], v32 src0_sel:WORD_1
	v_cvt_pk_f32_fp8_e32 v[166:167], v33
	v_cvt_pk_f32_fp8_sdwa v[168:169], v33 src0_sel:WORD_1
	v_cvt_pk_f32_fp8_e32 v[170:171], v34
	v_cvt_pk_f32_fp8_sdwa v[172:173], v34 src0_sel:WORD_1
	v_cvt_pk_f32_fp8_e32 v[174:175], v35
	v_cvt_pk_f32_fp8_sdwa v[176:177], v35 src0_sel:WORD_1
	v_lshl_add_u32 v230, v136, 7, v226
	global_load_dwordx4 v[32:35], v230, s[20:21]
	v_pk_fma_f32 v[194:195], v[152:153], v[162:163], v[194:195] op_sel_hi:[0,1,1]
	v_pk_fma_f32 v[196:197], v[152:153], v[164:165], v[196:197] op_sel_hi:[0,1,1]
	v_pk_fma_f32 v[198:199], v[152:153], v[166:167], v[198:199] op_sel_hi:[0,1,1]
	v_pk_fma_f32 v[200:201], v[152:153], v[168:169], v[200:201] op_sel_hi:[0,1,1]
	v_pk_fma_f32 v[202:203], v[152:153], v[170:171], v[202:203] op_sel_hi:[0,1,1]
	v_pk_fma_f32 v[204:205], v[152:153], v[172:173], v[204:205] op_sel_hi:[0,1,1]
	v_pk_fma_f32 v[206:207], v[152:153], v[174:175], v[206:207] op_sel_hi:[0,1,1]
	v_pk_fma_f32 v[208:209], v[152:153], v[176:177], v[208:209] op_sel_hi:[0,1,1]
	v_cvt_pk_f32_fp8_e32 v[178:179], v36
	v_cvt_pk_f32_fp8_sdwa v[180:181], v36 src0_sel:WORD_1
	v_cvt_pk_f32_fp8_e32 v[182:183], v37
; __device__ __forceinline__ void phase_peer_out(const Params& P, int l) {
;     ...
;         u32x4 vq[16]; float cf[16];
; #pragma unroll
;         for (int i = 0; i < 16; ++i) { vq[i] = *(const u32x4*)(PV + ((unsigned)en[i] * 128u + lo)); cf[i] = cfp[(size_t)t * 128 + 8 * i]; }
;         float* yp = P.out + (size_t)t * DM + 128 * s + 16 * sub + ((lane & 16) ? 8 : 0) + ((lane & 32) ? 4 : 0);
;         const f32x4 xo = *(const f32x4*)yp;
;         { const int tn = (t + nslots < T) ? t + nslots : t;
; #pragma unroll
;           for (int i = 0; i < 16; ++i) en[i] = eidx[(size_t)tn * 128 + 8 * i]; }
;         __builtin_amdgcn_sched_barrier(0);
;         f32x2 acc2[8];
; #pragma unroll
;         for (int c = 0; c < 8; ++c) acc2[c] = (f32x2){0.f, 0.f};
; #pragma unroll
;         for (int i = 0; i < 16; ++i) { f32x2 vd[8]; fp8x16_dec2(vq[i], vd); const f32x2 c2 = {cf[i], cf[i]};
; #pragma unroll
;             for (int c = 0; c < 8; ++c) acc2[c] = __builtin_elementwise_fma(c2, vd[c], acc2[c]);
;             __builtin_amdgcn_sched_barrier(0); }
	v_cvt_pk_f32_fp8_sdwa v[184:185], v37 src0_sel:WORD_1
	v_cvt_pk_f32_fp8_e32 v[186:187], v38
	v_cvt_pk_f32_fp8_sdwa v[188:189], v38 src0_sel:WORD_1
	v_cvt_pk_f32_fp8_e32 v[190:191], v39
	v_cvt_pk_f32_fp8_sdwa v[192:193], v39 src0_sel:WORD_1
	v_lshl_add_u32 v231, v137, 7, v226
	global_load_dwordx4 v[36:39], v231, s[20:21]
	v_pk_fma_f32 v[194:195], v[152:153], v[178:179], v[194:195] op_sel:[1,0,0] op_sel_hi:[1,1,1]
	v_pk_fma_f32 v[196:197], v[152:153], v[180:181], v[196:197] op_sel:[1,0,0] op_sel_hi:[1,1,1]
	v_pk_fma_f32 v[198:199], v[152:153], v[182:183], v[198:199] op_sel:[1,0,0] op_sel_hi:[1,1,1]
	v_pk_fma_f32 v[200:201], v[152:153], v[184:185], v[200:201] op_sel:[1,0,0] op_sel_hi:[1,1,1]
	v_pk_fma_f32 v[202:203], v[152:153], v[186:187], v[202:203] op_sel:[1,0,0] op_sel_hi:[1,1,1]
	v_pk_fma_f32 v[204:205], v[152:153], v[188:189], v[204:205] op_sel:[1,0,0] op_sel_hi:[1,1,1]
	v_pk_fma_f32 v[206:207], v[152:153], v[190:191], v[206:207] op_sel:[1,0,0] op_sel_hi:[1,1,1]
	v_pk_fma_f32 v[208:209], v[152:153], v[192:193], v[208:209] op_sel:[1,0,0] op_sel_hi:[1,1,1]
	v_cvt_pk_f32_fp8_e32 v[162:163], v40
	v_cvt_pk_f32_fp8_sdwa v[164:165], v40 src0_sel:WORD_1
	v_cvt_pk_f32_fp8_e32 v[166:167], v41
	v_cvt_pk_f32_fp8_sdwa v[168:169], v41 src0_sel:WORD_1
	v_cvt_pk_f32_fp8_e32 v[170:171], v42
	v_cvt_pk_f32_fp8_sdwa v[172:173], v42 src0_sel:WORD_1
	v_cvt_pk_f32_fp8_e32 v[174:175], v43
	v_cvt_pk_f32_fp8_sdwa v[176:177], v43 src0_sel:WORD_1
	v_lshl_add_u32 v230, v138, 7, v226
	global_load_dwordx4 v[40:43], v230, s[20:21]
	v_pk_fma_f32 v[194:195], v[154:155], v[162:163], v[194:195] op_sel_hi:[0,1,1]
	v_pk_fma_f32 v[196:197], v[154:155], v[164:165], v[196:197] op_sel_hi:[0,1,1]
	v_pk_fma_f32 v[198:199], v[154:155], v[166:167], v[198:199] op_sel_hi:[0,1,1]
	v_pk_fma_f32 v[200:201], v[154:155], v[168:169], v[200:201] op_sel_hi:[0,1,1]
	v_pk_fma_f32 v[202:203], v[154:155], v[170:171], v[202:203] op_sel_hi:[0,1,1]
	v_pk_fma_f32 v[204:205], v[154:155], v[172:173], v[204:205] op_sel_hi:[0,1,1]
	v_pk_fma_f32 v[206:207], v[154:155], v[174:175], v[206:207] op_sel_hi:[0,1,1]
	v_pk_fma_f32 v[208:209], v[154:155], v[176:177], v[208:209] op_sel_hi:[0,1,1]
	v_cvt_pk_f32_fp8_e32 v[178:179], v44
	v_cvt_pk_f32_fp8_sdwa v[180:181], v44 src0_sel:WORD_1
	v_cvt_pk_f32_fp8_e32 v[182:183], v45
	v_cvt_pk_f32_fp8_sdwa v[184:185], v45 src0_sel:WORD_1
	v_cvt_pk_f32_fp8_e32 v[186:187], v46
	v_cvt_pk_f32_fp8_sdwa v[188:189], v46 src0_sel:WORD_1
	v_cvt_pk_f32_fp8_e32 v[190:191], v47
	v_cvt_pk_f32_fp8_sdwa v[192:193], v47 src0_sel:WORD_1
	v_lshl_add_u32 v231, v139, 7, v226
	global_load_dwordx4 v[44:47], v231, s[20:21]
	v_pk_fma_f32 v[194:195], v[154:155], v[178:179], v[194:195] op_sel:[1,0,0] op_sel_hi:[1,1,1]
	v_pk_fma_f32 v[196:197], v[154:155], v[180:181], v[196:197] op_sel:[1,0,0] op_sel_hi:[1,1,1]
	v_pk_fma_f32 v[198:199], v[154:155], v[182:183], v[198:199] op_sel:[1,0,0] op_sel_hi:[1,1,1]
	v_pk_fma_f32 v[200:201], v[154:155], v[184:185], v[200:201] op_sel:[1,0,0] op_sel_hi:[1,1,1]
	v_pk_fma_f32 v[202:203], v[154:155], v[186:187], v[202:203] op_sel:[1,0,0] op_sel_hi:[1,1,1]
	v_pk_fma_f32 v[204:205], v[154:155], v[188:189], v[204:205] op_sel:[1,0,0] op_sel_hi:[1,1,1]
	v_pk_fma_f32 v[206:207], v[154:155], v[190:191], v[206:207] op_sel:[1,0,0] op_sel_hi:[1,1,1]
	v_pk_fma_f32 v[208:209], v[154:155], v[192:193], v[208:209] op_sel:[1,0,0] op_sel_hi:[1,1,1]
	v_cvt_pk_f32_fp8_e32 v[162:163], v48
	v_cvt_pk_f32_fp8_sdwa v[164:165], v48 src0_sel:WORD_1
	v_cvt_pk_f32_fp8_e32 v[166:167], v49
	v_cvt_pk_f32_fp8_sdwa v[168:169], v49 src0_sel:WORD_1
	v_cvt_pk_f32_fp8_e32 v[170:171], v50
	v_cvt_pk_f32_fp8_sdwa v[172:173], v50 src0_sel:WORD_1
	v_cvt_pk_f32_fp8_e32 v[174:175], v51
	v_cvt_pk_f32_fp8_sdwa v[176:177], v51 src0_sel:WORD_1
	v_lshl_add_u32 v230, v140, 7, v226
	global_load_dwordx4 v[48:51], v230, s[20:21]
	v_pk_fma_f32 v[194:195], v[156:157], v[162:163], v[194:195] op_sel_hi:[0,1,1]
	v_pk_fma_f32 v[196:197], v[156:157], v[164:165], v[196:197] op_sel_hi:[0,1,1]
	v_pk_fma_f32 v[198:199], v[156:157], v[166:167], v[198:199] op_sel_hi:[0,1,1]
	v_pk_fma_f32 v[200:201], v[156:157], v[168:169], v[200:201] op_sel_hi:[0,1,1]
	v_pk_fma_f32 v[202:203], v[156:157], v[170:171], v[202:203] op_sel_hi:[0,1,1]
	v_pk_fma_f32 v[204:205], v[156:157], v[172:173], v[204:205] op_sel_hi:[0,1,1]
	v_pk_fma_f32 v[206:207], v[156:157], v[174:175], v[206:207] op_sel_hi:[0,1,1]
	v_pk_fma_f32 v[208:209], v[156:157], v[176:177], v[208:209] op_sel_hi:[0,1,1]
	v_cvt_pk_f32_fp8_e32 v[178:179], v52
	v_cvt_pk_f32_fp8_sdwa v[180:181], v52 src0_sel:WORD_1
	v_cvt_pk_f32_fp8_e32 v[182:183], v53
	v_cvt_pk_f32_fp8_sdwa v[184:185], v53 src0_sel:WORD_1
	v_cvt_pk_f32_fp8_e32 v[186:187], v54
	v_cvt_pk_f32_fp8_sdwa v[188:189], v54 src0_sel:WORD_1
	v_cvt_pk_f32_fp8_e32 v[190:191], v55
	v_cvt_pk_f32_fp8_sdwa v[192:193], v55 src0_sel:WORD_1
	v_lshl_add_u32 v231, v141, 7, v226
	global_load_dwordx4 v[52:55], v231, s[20:21]
	v_pk_fma_f32 v[194:195], v[156:157], v[178:179], v[194:195] op_sel:[1,0,0] op_sel_hi:[1,1,1]
	v_pk_fma_f32 v[196:197], v[156:157], v[180:181], v[196:197] op_sel:[1,0,0] op_sel_hi:[1,1,1]
	v_pk_fma_f32 v[198:199], v[156:157], v[182:183], v[198:199] op_sel:[1,0,0] op_sel_hi:[1,1,1]
	v_pk_fma_f32 v[200:201], v[156:157], v[184:185], v[200:201] op_sel:[1,0,0] op_sel_hi:[1,1,1]
	v_pk_fma_f32 v[202:203], v[156:157], v[186:187], v[202:203] op_sel:[1,0,0] op_sel_hi:[1,1,1]
	v_pk_fma_f32 v[204:205], v[156:157], v[188:189], v[204:205] op_sel:[1,0,0] op_sel_hi:[1,1,1]
	v_pk_fma_f32 v[206:207], v[156:157], v[190:191], v[206:207] op_sel:[1,0,0] op_sel_hi:[1,1,1]
	v_pk_fma_f32 v[208:209], v[156:157], v[192:193], v[208:209] op_sel:[1,0,0] op_sel_hi:[1,1,1]
; __device__ __forceinline__ unsigned cvt_pk_bf16(float lo, float hi) { const f32x2 v = {lo, hi}; return __builtin_bit_cast(unsigned, __builtin_convertvector(v, bf16x2v)); }
; template <int CTRL> __device__ __forceinline__ float dppf(float v) { return __builtin_bit_cast(float, __builtin_amdgcn_update_dpp(0, __builtin_bit_cast(int, v), CTRL, 0xF, 0xF, true)); }
; __device__ __forceinline__ void phase_peer_out(const Params& P, int l) {
;     ...
;         u32x4 vq[16]; float cf[16];
; #pragma unroll
;         for (int i = 0; i < 16; ++i) { vq[i] = *(const u32x4*)(PV + ((unsigned)en[i] * 128u + lo)); cf[i] = cfp[(size_t)t * 128 + 8 * i]; }
;         float* yp = P.out + (size_t)t * DM + 128 * s + 16 * sub + ((lane & 16) ? 8 : 0) + ((lane & 32) ? 4 : 0);
;         const f32x4 xo = *(const f32x4*)yp;
;         { const int tn = (t + nslots < T) ? t + nslots : t;
; #pragma unroll
;           for (int i = 0; i < 16; ++i) en[i] = eidx[(size_t)tn * 128 + 8 * i]; }
;     ...
;         for (int i = 0; i < 16; ++i) { f32x2 vd[8]; fp8x16_dec2(vq[i], vd); const f32x2 c2 = {cf[i], cf[i]};
; #pragma unroll
;             for (int c = 0; c < 8; ++c) acc2[c] = __builtin_elementwise_fma(c2, vd[c], acc2[c]);
;             __builtin_amdgcn_sched_barrier(0); }
;         float acc[16];
; #pragma unroll
;         for (int c = 0; c < 8; ++c) { acc[2 * c] = acc2[c].x; acc[2 * c + 1] = acc2[c].y; }
; #pragma unroll
;         for (int c = 0; c < 16; ++c) acc[c] += dppf<0x128>(acc[c]);
;         float r8[8], r4[4];
;         { const bool up = (lane & 16) != 0;
; #pragma unroll
;           for (int c = 0; c < 8; ++c) { const float send = up ? acc[c] : acc[c + 8], keep = up ? acc[c + 8] : acc[c]; r8[c] = keep + __shfl_xor(send, 16); } }
;         { const bool up = (lane & 32) != 0;
; #pragma unroll
;           for (int c = 0; c < 4; ++c) { const float send = up ? r8[c] : r8[c + 4], keep = up ? r8[c + 4] : r8[c]; r4[c] = keep + __shfl_xor(send, 32); } }
;         if ((lane & 8) == 0) { u32x2 w; w.x = cvt_pk_bf16(DN_ALPHA * xo[0] + r4[0], DN_ALPHA * xo[1] + r4[1]); w.y = cvt_pk_bf16(DN_ALPHA * xo[2] + r4[2], DN_ALPHA * xo[3] + r4[3]);
;             *(u32x2*)((bf16_t*)(P.ws + WS_R0) + (yp - P.out)) = w; }
	v_cvt_pk_f32_fp8_e32 v[162:163], v56
	v_cvt_pk_f32_fp8_sdwa v[164:165], v56 src0_sel:WORD_1
	v_cvt_pk_f32_fp8_e32 v[166:167], v57
	v_cvt_pk_f32_fp8_sdwa v[168:169], v57 src0_sel:WORD_1
	v_cvt_pk_f32_fp8_e32 v[170:171], v58
	v_cvt_pk_f32_fp8_sdwa v[172:173], v58 src0_sel:WORD_1
	v_cvt_pk_f32_fp8_e32 v[174:175], v59
	v_cvt_pk_f32_fp8_sdwa v[176:177], v59 src0_sel:WORD_1
	v_lshl_add_u32 v230, v142, 7, v226
	global_load_dwordx4 v[56:59], v230, s[20:21]
	v_pk_fma_f32 v[194:195], v[158:159], v[162:163], v[194:195] op_sel_hi:[0,1,1]
	v_pk_fma_f32 v[196:197], v[158:159], v[164:165], v[196:197] op_sel_hi:[0,1,1]
	v_pk_fma_f32 v[198:199], v[158:159], v[166:167], v[198:199] op_sel_hi:[0,1,1]
	v_pk_fma_f32 v[200:201], v[158:159], v[168:169], v[200:201] op_sel_hi:[0,1,1]
	v_pk_fma_f32 v[202:203], v[158:159], v[170:171], v[202:203] op_sel_hi:[0,1,1]
	v_pk_fma_f32 v[204:205], v[158:159], v[172:173], v[204:205] op_sel_hi:[0,1,1]
	v_pk_fma_f32 v[206:207], v[158:159], v[174:175], v[206:207] op_sel_hi:[0,1,1]
	v_pk_fma_f32 v[208:209], v[158:159], v[176:177], v[208:209] op_sel_hi:[0,1,1]
	v_cvt_pk_f32_fp8_e32 v[178:179], v60
	v_cvt_pk_f32_fp8_sdwa v[180:181], v60 src0_sel:WORD_1
	v_cvt_pk_f32_fp8_e32 v[182:183], v61
	v_cvt_pk_f32_fp8_sdwa v[184:185], v61 src0_sel:WORD_1
	v_cvt_pk_f32_fp8_e32 v[186:187], v62
	v_cvt_pk_f32_fp8_sdwa v[188:189], v62 src0_sel:WORD_1
	v_cvt_pk_f32_fp8_e32 v[190:191], v63
	v_cvt_pk_f32_fp8_sdwa v[192:193], v63 src0_sel:WORD_1
	v_lshl_add_u32 v231, v143, 7, v226
	global_load_dwordx4 v[60:63], v231, s[20:21]
	v_pk_fma_f32 v[194:195], v[158:159], v[178:179], v[194:195] op_sel:[1,0,0] op_sel_hi:[1,1,1]
	v_pk_fma_f32 v[196:197], v[158:159], v[180:181], v[196:197] op_sel:[1,0,0] op_sel_hi:[1,1,1]
	v_pk_fma_f32 v[198:199], v[158:159], v[182:183], v[198:199] op_sel:[1,0,0] op_sel_hi:[1,1,1]
	v_pk_fma_f32 v[200:201], v[158:159], v[184:185], v[200:201] op_sel:[1,0,0] op_sel_hi:[1,1,1]
	v_pk_fma_f32 v[202:203], v[158:159], v[186:187], v[202:203] op_sel:[1,0,0] op_sel_hi:[1,1,1]
	v_pk_fma_f32 v[204:205], v[158:159], v[188:189], v[204:205] op_sel:[1,0,0] op_sel_hi:[1,1,1]
	v_pk_fma_f32 v[206:207], v[158:159], v[190:191], v[206:207] op_sel:[1,0,0] op_sel_hi:[1,1,1]
	v_pk_fma_f32 v[208:209], v[158:159], v[192:193], v[208:209] op_sel:[1,0,0] op_sel_hi:[1,1,1]
	s_nop 1
	v_add_f32_dpp v194, v194, v194 row_ror:8 row_mask:0xf bank_mask:0xf bound_ctrl:1
	v_add_f32_dpp v195, v195, v195 row_ror:8 row_mask:0xf bank_mask:0xf bound_ctrl:1
	v_add_f32_dpp v196, v196, v196 row_ror:8 row_mask:0xf bank_mask:0xf bound_ctrl:1
	v_add_f32_dpp v197, v197, v197 row_ror:8 row_mask:0xf bank_mask:0xf bound_ctrl:1
	v_add_f32_dpp v198, v198, v198 row_ror:8 row_mask:0xf bank_mask:0xf bound_ctrl:1
	v_add_f32_dpp v199, v199, v199 row_ror:8 row_mask:0xf bank_mask:0xf bound_ctrl:1
	v_add_f32_dpp v200, v200, v200 row_ror:8 row_mask:0xf bank_mask:0xf bound_ctrl:1
	v_add_f32_dpp v201, v201, v201 row_ror:8 row_mask:0xf bank_mask:0xf bound_ctrl:1
	v_add_f32_dpp v202, v202, v202 row_ror:8 row_mask:0xf bank_mask:0xf bound_ctrl:1
	v_add_f32_dpp v203, v203, v203 row_ror:8 row_mask:0xf bank_mask:0xf bound_ctrl:1
	v_add_f32_dpp v204, v204, v204 row_ror:8 row_mask:0xf bank_mask:0xf bound_ctrl:1
	v_add_f32_dpp v205, v205, v205 row_ror:8 row_mask:0xf bank_mask:0xf bound_ctrl:1
	v_add_f32_dpp v206, v206, v206 row_ror:8 row_mask:0xf bank_mask:0xf bound_ctrl:1
	v_add_f32_dpp v207, v207, v207 row_ror:8 row_mask:0xf bank_mask:0xf bound_ctrl:1
	v_add_f32_dpp v208, v208, v208 row_ror:8 row_mask:0xf bank_mask:0xf bound_ctrl:1
	v_add_f32_dpp v209, v209, v209 row_ror:8 row_mask:0xf bank_mask:0xf bound_ctrl:1
	s_nop 1
	v_permlane16_swap_b32 v194, v202
	v_permlane16_swap_b32 v195, v203
	v_permlane16_swap_b32 v196, v204
	v_permlane16_swap_b32 v197, v205
	v_permlane16_swap_b32 v198, v206
	v_permlane16_swap_b32 v199, v207
	v_permlane16_swap_b32 v200, v208
	v_permlane16_swap_b32 v201, v209
	v_add_f32_e32 v194, v194, v202
	v_add_f32_e32 v195, v195, v203
	v_add_f32_e32 v196, v196, v204
	v_add_f32_e32 v197, v197, v205
	v_add_f32_e32 v198, v198, v206
	v_add_f32_e32 v199, v199, v207
	v_add_f32_e32 v200, v200, v208
	v_add_f32_e32 v201, v201, v209
	s_nop 1
	v_permlane32_swap_b32 v194, v198
	v_permlane32_swap_b32 v195, v199
	v_permlane32_swap_b32 v196, v200
	v_permlane32_swap_b32 v197, v201
	v_add_f32_e32 v194, v194, v198
	v_add_f32_e32 v195, v195, v199
	v_add_f32_e32 v196, v196, v200
	v_add_f32_e32 v197, v197, v201
	v_fma_f32 v194, v210, s10, v194
	v_fma_f32 v195, v211, s10, v195
	v_fma_f32 v196, v212, s10, v196
	v_fma_f32 v197, v213, s10, v197
	v_cvt_pk_bf16_f32 v236, v194, v195
	v_cvt_pk_bf16_f32 v237, v196, v197
	s_lshl_b32 s29, s28, 19
	s_add_u32 s30, s6, s29
	s_addc_u32 s31, s7, 0
	s_mov_b64 exec, s[8:9]
	global_store_dwordx2 v228, v[236:237], s[30:31]
	s_mov_b64 exec, -1
	s_waitcnt vmcnt(17)
	ds_write2_b32 v232, v218, v219 offset1:16
	ds_write2_b32 v232, v222, v223 offset0:128 offset1:144
	s_add_u32 s29, s28, 4
	s_min_u32 s29, s29, 0x7f
	s_lshl_b32 s29, s29, 17
	s_add_u32 s30, s22, s29
	s_addc_u32 s31, s23, 0
	global_load_dwordx2 v[220:221], v227, s[30:31]
	s_add_u32 s29, s28, 2
	s_min_u32 s29, s29, 0x7f
	s_lshl_b32 s29, s29, 17
	s_add_u32 s30, s24, s29
	s_addc_u32 s31, s25, 0
	global_load_dwordx2 v[224:225], v227, s[30:31]
	s_add_u32 s29, s28, 2
	s_min_u32 s29, s29, 0x7f
	s_lshl_b32 s29, s29, 20
	s_add_u32 s30, s4, s29
	s_addc_u32 s31, s5, 0
	global_load_dwordx4 v[210:213], v229, s[30:31]
	ds_read_b128 v[128:131], v233
	ds_read_b128 v[132:135], v233 offset:16
	ds_read_b128 v[136:139], v233 offset:32
	ds_read_b128 v[140:143], v233 offset:48
	ds_read_b128 v[144:147], v233 offset:512
	ds_read_b128 v[148:151], v233 offset:528
	ds_read_b128 v[152:155], v233 offset:544
	ds_read_b128 v[156:159], v233 offset:560
	s_waitcnt lgkmcnt(0)
; __device__ __forceinline__ void phase_peer_out(const Params& P, int l) {
;     ...
;         u32x4 vq[16]; float cf[16];
; #pragma unroll
;         for (int i = 0; i < 16; ++i) { vq[i] = *(const u32x4*)(PV + ((unsigned)en[i] * 128u + lo)); cf[i] = cfp[(size_t)t * 128 + 8 * i]; }
;         float* yp = P.out + (size_t)t * DM + 128 * s + 16 * sub + ((lane & 16) ? 8 : 0) + ((lane & 32) ? 4 : 0);
;         const f32x4 xo = *(const f32x4*)yp;
;         { const int tn = (t + nslots < T) ? t + nslots : t;
; #pragma unroll
;           for (int i = 0; i < 16; ++i) en[i] = eidx[(size_t)tn * 128 + 8 * i]; }
;         __builtin_amdgcn_sched_barrier(0);
;         f32x2 acc2[8];
; #pragma unroll
;         for (int c = 0; c < 8; ++c) acc2[c] = (f32x2){0.f, 0.f};
; #pragma unroll
;         for (int i = 0; i < 16; ++i) { f32x2 vd[8]; fp8x16_dec2(vq[i], vd); const f32x2 c2 = {cf[i], cf[i]};
; #pragma unroll
;             for (int c = 0; c < 8; ++c) acc2[c] = __builtin_elementwise_fma(c2, vd[c], acc2[c]);
;             __builtin_amdgcn_sched_barrier(0); }
	v_cvt_pk_f32_fp8_e32 v[162:163], v64
	v_cvt_pk_f32_fp8_sdwa v[164:165], v64 src0_sel:WORD_1
	v_cvt_pk_f32_fp8_e32 v[166:167], v65
	v_cvt_pk_f32_fp8_sdwa v[168:169], v65 src0_sel:WORD_1
	v_cvt_pk_f32_fp8_e32 v[170:171], v66
	v_cvt_pk_f32_fp8_sdwa v[172:173], v66 src0_sel:WORD_1
	v_cvt_pk_f32_fp8_e32 v[174:175], v67
	v_cvt_pk_f32_fp8_sdwa v[176:177], v67 src0_sel:WORD_1
	v_lshl_add_u32 v230, v128, 7, v226
	global_load_dwordx4 v[64:67], v230, s[20:21]
	v_pk_fma_f32 v[194:195], v[144:145], v[162:163], 0 op_sel_hi:[0,1,0]
	v_pk_fma_f32 v[196:197], v[144:145], v[164:165], 0 op_sel_hi:[0,1,0]
	v_pk_fma_f32 v[198:199], v[144:145], v[166:167], 0 op_sel_hi:[0,1,0]
	v_pk_fma_f32 v[200:201], v[144:145], v[168:169], 0 op_sel_hi:[0,1,0]
	v_pk_fma_f32 v[202:203], v[144:145], v[170:171], 0 op_sel_hi:[0,1,0]
	v_pk_fma_f32 v[204:205], v[144:145], v[172:173], 0 op_sel_hi:[0,1,0]
	v_pk_fma_f32 v[206:207], v[144:145], v[174:175], 0 op_sel_hi:[0,1,0]
	v_pk_fma_f32 v[208:209], v[144:145], v[176:177], 0 op_sel_hi:[0,1,0]
	v_cvt_pk_f32_fp8_e32 v[178:179], v68
	v_cvt_pk_f32_fp8_sdwa v[180:181], v68 src0_sel:WORD_1
	v_cvt_pk_f32_fp8_e32 v[182:183], v69
	v_cvt_pk_f32_fp8_sdwa v[184:185], v69 src0_sel:WORD_1
	v_cvt_pk_f32_fp8_e32 v[186:187], v70
	v_cvt_pk_f32_fp8_sdwa v[188:189], v70 src0_sel:WORD_1
	v_cvt_pk_f32_fp8_e32 v[190:191], v71
	v_cvt_pk_f32_fp8_sdwa v[192:193], v71 src0_sel:WORD_1
	v_lshl_add_u32 v231, v129, 7, v226
	global_load_dwordx4 v[68:71], v231, s[20:21]
	v_pk_fma_f32 v[194:195], v[144:145], v[178:179], v[194:195] op_sel:[1,0,0] op_sel_hi:[1,1,1]
	v_pk_fma_f32 v[196:197], v[144:145], v[180:181], v[196:197] op_sel:[1,0,0] op_sel_hi:[1,1,1]
	v_pk_fma_f32 v[198:199], v[144:145], v[182:183], v[198:199] op_sel:[1,0,0] op_sel_hi:[1,1,1]
	v_pk_fma_f32 v[200:201], v[144:145], v[184:185], v[200:201] op_sel:[1,0,0] op_sel_hi:[1,1,1]
	v_pk_fma_f32 v[202:203], v[144:145], v[186:187], v[202:203] op_sel:[1,0,0] op_sel_hi:[1,1,1]
	v_pk_fma_f32 v[204:205], v[144:145], v[188:189], v[204:205] op_sel:[1,0,0] op_sel_hi:[1,1,1]
	v_pk_fma_f32 v[206:207], v[144:145], v[190:191], v[206:207] op_sel:[1,0,0] op_sel_hi:[1,1,1]
	v_pk_fma_f32 v[208:209], v[144:145], v[192:193], v[208:209] op_sel:[1,0,0] op_sel_hi:[1,1,1]
	v_cvt_pk_f32_fp8_e32 v[162:163], v72
	v_cvt_pk_f32_fp8_sdwa v[164:165], v72 src0_sel:WORD_1
	v_cvt_pk_f32_fp8_e32 v[166:167], v73
	v_cvt_pk_f32_fp8_sdwa v[168:169], v73 src0_sel:WORD_1
	v_cvt_pk_f32_fp8_e32 v[170:171], v74
	v_cvt_pk_f32_fp8_sdwa v[172:173], v74 src0_sel:WORD_1
	v_cvt_pk_f32_fp8_e32 v[174:175], v75
	v_cvt_pk_f32_fp8_sdwa v[176:177], v75 src0_sel:WORD_1
	v_lshl_add_u32 v230, v130, 7, v226
	global_load_dwordx4 v[72:75], v230, s[20:21]
	v_pk_fma_f32 v[194:195], v[146:147], v[162:163], v[194:195] op_sel_hi:[0,1,1]
	v_pk_fma_f32 v[196:197], v[146:147], v[164:165], v[196:197] op_sel_hi:[0,1,1]
	v_pk_fma_f32 v[198:199], v[146:147], v[166:167], v[198:199] op_sel_hi:[0,1,1]
	v_pk_fma_f32 v[200:201], v[146:147], v[168:169], v[200:201] op_sel_hi:[0,1,1]
	v_pk_fma_f32 v[202:203], v[146:147], v[170:171], v[202:203] op_sel_hi:[0,1,1]
	v_pk_fma_f32 v[204:205], v[146:147], v[172:173], v[204:205] op_sel_hi:[0,1,1]
	v_pk_fma_f32 v[206:207], v[146:147], v[174:175], v[206:207] op_sel_hi:[0,1,1]
	v_pk_fma_f32 v[208:209], v[146:147], v[176:177], v[208:209] op_sel_hi:[0,1,1]
	v_cvt_pk_f32_fp8_e32 v[178:179], v76
	v_cvt_pk_f32_fp8_sdwa v[180:181], v76 src0_sel:WORD_1
	v_cvt_pk_f32_fp8_e32 v[182:183], v77
	v_cvt_pk_f32_fp8_sdwa v[184:185], v77 src0_sel:WORD_1
	v_cvt_pk_f32_fp8_e32 v[186:187], v78
	v_cvt_pk_f32_fp8_sdwa v[188:189], v78 src0_sel:WORD_1
	v_cvt_pk_f32_fp8_e32 v[190:191], v79
	v_cvt_pk_f32_fp8_sdwa v[192:193], v79 src0_sel:WORD_1
	v_lshl_add_u32 v231, v131, 7, v226
	global_load_dwordx4 v[76:79], v231, s[20:21]
	v_pk_fma_f32 v[194:195], v[146:147], v[178:179], v[194:195] op_sel:[1,0,0] op_sel_hi:[1,1,1]
	v_pk_fma_f32 v[196:197], v[146:147], v[180:181], v[196:197] op_sel:[1,0,0] op_sel_hi:[1,1,1]
	v_pk_fma_f32 v[198:199], v[146:147], v[182:183], v[198:199] op_sel:[1,0,0] op_sel_hi:[1,1,1]
	v_pk_fma_f32 v[200:201], v[146:147], v[184:185], v[200:201] op_sel:[1,0,0] op_sel_hi:[1,1,1]
	v_pk_fma_f32 v[202:203], v[146:147], v[186:187], v[202:203] op_sel:[1,0,0] op_sel_hi:[1,1,1]
	v_pk_fma_f32 v[204:205], v[146:147], v[188:189], v[204:205] op_sel:[1,0,0] op_sel_hi:[1,1,1]
	v_pk_fma_f32 v[206:207], v[146:147], v[190:191], v[206:207] op_sel:[1,0,0] op_sel_hi:[1,1,1]
	v_pk_fma_f32 v[208:209], v[146:147], v[192:193], v[208:209] op_sel:[1,0,0] op_sel_hi:[1,1,1]
	v_cvt_pk_f32_fp8_e32 v[162:163], v80
	v_cvt_pk_f32_fp8_sdwa v[164:165], v80 src0_sel:WORD_1
	v_cvt_pk_f32_fp8_e32 v[166:167], v81
	v_cvt_pk_f32_fp8_sdwa v[168:169], v81 src0_sel:WORD_1
	v_cvt_pk_f32_fp8_e32 v[170:171], v82
	v_cvt_pk_f32_fp8_sdwa v[172:173], v82 src0_sel:WORD_1
	v_cvt_pk_f32_fp8_e32 v[174:175], v83
	v_cvt_pk_f32_fp8_sdwa v[176:177], v83 src0_sel:WORD_1
	v_lshl_add_u32 v230, v132, 7, v226
	global_load_dwordx4 v[80:83], v230, s[20:21]
	v_pk_fma_f32 v[194:195], v[148:149], v[162:163], v[194:195] op_sel_hi:[0,1,1]
	v_pk_fma_f32 v[196:197], v[148:149], v[164:165], v[196:197] op_sel_hi:[0,1,1]
	v_pk_fma_f32 v[198:199], v[148:149], v[166:167], v[198:199] op_sel_hi:[0,1,1]
	v_pk_fma_f32 v[200:201], v[148:149], v[168:169], v[200:201] op_sel_hi:[0,1,1]
	v_pk_fma_f32 v[202:203], v[148:149], v[170:171], v[202:203] op_sel_hi:[0,1,1]
	v_pk_fma_f32 v[204:205], v[148:149], v[172:173], v[204:205] op_sel_hi:[0,1,1]
	v_pk_fma_f32 v[206:207], v[148:149], v[174:175], v[206:207] op_sel_hi:[0,1,1]
	v_pk_fma_f32 v[208:209], v[148:149], v[176:177], v[208:209] op_sel_hi:[0,1,1]
	v_cvt_pk_f32_fp8_e32 v[178:179], v84
; __device__ __forceinline__ void phase_peer_out(const Params& P, int l) {
;     ...
;         u32x4 vq[16]; float cf[16];
; #pragma unroll
;         for (int i = 0; i < 16; ++i) { vq[i] = *(const u32x4*)(PV + ((unsigned)en[i] * 128u + lo)); cf[i] = cfp[(size_t)t * 128 + 8 * i]; }
;         float* yp = P.out + (size_t)t * DM + 128 * s + 16 * sub + ((lane & 16) ? 8 : 0) + ((lane & 32) ? 4 : 0);
;         const f32x4 xo = *(const f32x4*)yp;
;         { const int tn = (t + nslots < T) ? t + nslots : t;
; #pragma unroll
;           for (int i = 0; i < 16; ++i) en[i] = eidx[(size_t)tn * 128 + 8 * i]; }
;         __builtin_amdgcn_sched_barrier(0);
;         f32x2 acc2[8];
; #pragma unroll
;         for (int c = 0; c < 8; ++c) acc2[c] = (f32x2){0.f, 0.f};
; #pragma unroll
;         for (int i = 0; i < 16; ++i) { f32x2 vd[8]; fp8x16_dec2(vq[i], vd); const f32x2 c2 = {cf[i], cf[i]};
; #pragma unroll
;             for (int c = 0; c < 8; ++c) acc2[c] = __builtin_elementwise_fma(c2, vd[c], acc2[c]);
;             __builtin_amdgcn_sched_barrier(0); }
	v_cvt_pk_f32_fp8_sdwa v[180:181], v84 src0_sel:WORD_1
	v_cvt_pk_f32_fp8_e32 v[182:183], v85
	v_cvt_pk_f32_fp8_sdwa v[184:185], v85 src0_sel:WORD_1
	v_cvt_pk_f32_fp8_e32 v[186:187], v86
	v_cvt_pk_f32_fp8_sdwa v[188:189], v86 src0_sel:WORD_1
	v_cvt_pk_f32_fp8_e32 v[190:191], v87
	v_cvt_pk_f32_fp8_sdwa v[192:193], v87 src0_sel:WORD_1
	v_lshl_add_u32 v231, v133, 7, v226
	global_load_dwordx4 v[84:87], v231, s[20:21]
	v_pk_fma_f32 v[194:195], v[148:149], v[178:179], v[194:195] op_sel:[1,0,0] op_sel_hi:[1,1,1]
	v_pk_fma_f32 v[196:197], v[148:149], v[180:181], v[196:197] op_sel:[1,0,0] op_sel_hi:[1,1,1]
	v_pk_fma_f32 v[198:199], v[148:149], v[182:183], v[198:199] op_sel:[1,0,0] op_sel_hi:[1,1,1]
	v_pk_fma_f32 v[200:201], v[148:149], v[184:185], v[200:201] op_sel:[1,0,0] op_sel_hi:[1,1,1]
	v_pk_fma_f32 v[202:203], v[148:149], v[186:187], v[202:203] op_sel:[1,0,0] op_sel_hi:[1,1,1]
	v_pk_fma_f32 v[204:205], v[148:149], v[188:189], v[204:205] op_sel:[1,0,0] op_sel_hi:[1,1,1]
	v_pk_fma_f32 v[206:207], v[148:149], v[190:191], v[206:207] op_sel:[1,0,0] op_sel_hi:[1,1,1]
	v_pk_fma_f32 v[208:209], v[148:149], v[192:193], v[208:209] op_sel:[1,0,0] op_sel_hi:[1,1,1]
	v_cvt_pk_f32_fp8_e32 v[162:163], v88
	v_cvt_pk_f32_fp8_sdwa v[164:165], v88 src0_sel:WORD_1
	v_cvt_pk_f32_fp8_e32 v[166:167], v89
	v_cvt_pk_f32_fp8_sdwa v[168:169], v89 src0_sel:WORD_1
	v_cvt_pk_f32_fp8_e32 v[170:171], v90
	v_cvt_pk_f32_fp8_sdwa v[172:173], v90 src0_sel:WORD_1
	v_cvt_pk_f32_fp8_e32 v[174:175], v91
	v_cvt_pk_f32_fp8_sdwa v[176:177], v91 src0_sel:WORD_1
	v_lshl_add_u32 v230, v134, 7, v226
	global_load_dwordx4 v[88:91], v230, s[20:21]
	v_pk_fma_f32 v[194:195], v[150:151], v[162:163], v[194:195] op_sel_hi:[0,1,1]
	v_pk_fma_f32 v[196:197], v[150:151], v[164:165], v[196:197] op_sel_hi:[0,1,1]
	v_pk_fma_f32 v[198:199], v[150:151], v[166:167], v[198:199] op_sel_hi:[0,1,1]
	v_pk_fma_f32 v[200:201], v[150:151], v[168:169], v[200:201] op_sel_hi:[0,1,1]
	v_pk_fma_f32 v[202:203], v[150:151], v[170:171], v[202:203] op_sel_hi:[0,1,1]
	v_pk_fma_f32 v[204:205], v[150:151], v[172:173], v[204:205] op_sel_hi:[0,1,1]
	v_pk_fma_f32 v[206:207], v[150:151], v[174:175], v[206:207] op_sel_hi:[0,1,1]
	v_pk_fma_f32 v[208:209], v[150:151], v[176:177], v[208:209] op_sel_hi:[0,1,1]
	v_cvt_pk_f32_fp8_e32 v[178:179], v92
	v_cvt_pk_f32_fp8_sdwa v[180:181], v92 src0_sel:WORD_1
	v_cvt_pk_f32_fp8_e32 v[182:183], v93
	v_cvt_pk_f32_fp8_sdwa v[184:185], v93 src0_sel:WORD_1
	v_cvt_pk_f32_fp8_e32 v[186:187], v94
	v_cvt_pk_f32_fp8_sdwa v[188:189], v94 src0_sel:WORD_1
	v_cvt_pk_f32_fp8_e32 v[190:191], v95
	v_cvt_pk_f32_fp8_sdwa v[192:193], v95 src0_sel:WORD_1
	v_lshl_add_u32 v231, v135, 7, v226
	global_load_dwordx4 v[92:95], v231, s[20:21]
	v_pk_fma_f32 v[194:195], v[150:151], v[178:179], v[194:195] op_sel:[1,0,0] op_sel_hi:[1,1,1]
	v_pk_fma_f32 v[196:197], v[150:151], v[180:181], v[196:197] op_sel:[1,0,0] op_sel_hi:[1,1,1]
	v_pk_fma_f32 v[198:199], v[150:151], v[182:183], v[198:199] op_sel:[1,0,0] op_sel_hi:[1,1,1]
	v_pk_fma_f32 v[200:201], v[150:151], v[184:185], v[200:201] op_sel:[1,0,0] op_sel_hi:[1,1,1]
	v_pk_fma_f32 v[202:203], v[150:151], v[186:187], v[202:203] op_sel:[1,0,0] op_sel_hi:[1,1,1]
	v_pk_fma_f32 v[204:205], v[150:151], v[188:189], v[204:205] op_sel:[1,0,0] op_sel_hi:[1,1,1]
	v_pk_fma_f32 v[206:207], v[150:151], v[190:191], v[206:207] op_sel:[1,0,0] op_sel_hi:[1,1,1]
	v_pk_fma_f32 v[208:209], v[150:151], v[192:193], v[208:209] op_sel:[1,0,0] op_sel_hi:[1,1,1]
	v_cvt_pk_f32_fp8_e32 v[162:163], v96
	v_cvt_pk_f32_fp8_sdwa v[164:165], v96 src0_sel:WORD_1
	v_cvt_pk_f32_fp8_e32 v[166:167], v97
	v_cvt_pk_f32_fp8_sdwa v[168:169], v97 src0_sel:WORD_1
	v_cvt_pk_f32_fp8_e32 v[170:171], v98
	v_cvt_pk_f32_fp8_sdwa v[172:173], v98 src0_sel:WORD_1
	v_cvt_pk_f32_fp8_e32 v[174:175], v99
	v_cvt_pk_f32_fp8_sdwa v[176:177], v99 src0_sel:WORD_1
	v_lshl_add_u32 v230, v136, 7, v226
	global_load_dwordx4 v[96:99], v230, s[20:21]
	v_pk_fma_f32 v[194:195], v[152:153], v[162:163], v[194:195] op_sel_hi:[0,1,1]
	v_pk_fma_f32 v[196:197], v[152:153], v[164:165], v[196:197] op_sel_hi:[0,1,1]
	v_pk_fma_f32 v[198:199], v[152:153], v[166:167], v[198:199] op_sel_hi:[0,1,1]
	v_pk_fma_f32 v[200:201], v[152:153], v[168:169], v[200:201] op_sel_hi:[0,1,1]
	v_pk_fma_f32 v[202:203], v[152:153], v[170:171], v[202:203] op_sel_hi:[0,1,1]
	v_pk_fma_f32 v[204:205], v[152:153], v[172:173], v[204:205] op_sel_hi:[0,1,1]
	v_pk_fma_f32 v[206:207], v[152:153], v[174:175], v[206:207] op_sel_hi:[0,1,1]
	v_pk_fma_f32 v[208:209], v[152:153], v[176:177], v[208:209] op_sel_hi:[0,1,1]
	v_cvt_pk_f32_fp8_e32 v[178:179], v100
	v_cvt_pk_f32_fp8_sdwa v[180:181], v100 src0_sel:WORD_1
	v_cvt_pk_f32_fp8_e32 v[182:183], v101
	v_cvt_pk_f32_fp8_sdwa v[184:185], v101 src0_sel:WORD_1
	v_cvt_pk_f32_fp8_e32 v[186:187], v102
	v_cvt_pk_f32_fp8_sdwa v[188:189], v102 src0_sel:WORD_1
	v_cvt_pk_f32_fp8_e32 v[190:191], v103
	v_cvt_pk_f32_fp8_sdwa v[192:193], v103 src0_sel:WORD_1
	v_lshl_add_u32 v231, v137, 7, v226
	global_load_dwordx4 v[100:103], v231, s[20:21]
	v_pk_fma_f32 v[194:195], v[152:153], v[178:179], v[194:195] op_sel:[1,0,0] op_sel_hi:[1,1,1]
	v_pk_fma_f32 v[196:197], v[152:153], v[180:181], v[196:197] op_sel:[1,0,0] op_sel_hi:[1,1,1]
	v_pk_fma_f32 v[198:199], v[152:153], v[182:183], v[198:199] op_sel:[1,0,0] op_sel_hi:[1,1,1]
	v_pk_fma_f32 v[200:201], v[152:153], v[184:185], v[200:201] op_sel:[1,0,0] op_sel_hi:[1,1,1]
	v_pk_fma_f32 v[202:203], v[152:153], v[186:187], v[202:203] op_sel:[1,0,0] op_sel_hi:[1,1,1]
	v_pk_fma_f32 v[204:205], v[152:153], v[188:189], v[204:205] op_sel:[1,0,0] op_sel_hi:[1,1,1]
	v_pk_fma_f32 v[206:207], v[152:153], v[190:191], v[206:207] op_sel:[1,0,0] op_sel_hi:[1,1,1]
; __device__ __forceinline__ void phase_peer_out(const Params& P, int l) {
;     ...
;         u32x4 vq[16]; float cf[16];
; #pragma unroll
;         for (int i = 0; i < 16; ++i) { vq[i] = *(const u32x4*)(PV + ((unsigned)en[i] * 128u + lo)); cf[i] = cfp[(size_t)t * 128 + 8 * i]; }
;         float* yp = P.out + (size_t)t * DM + 128 * s + 16 * sub + ((lane & 16) ? 8 : 0) + ((lane & 32) ? 4 : 0);
;         const f32x4 xo = *(const f32x4*)yp;
;         { const int tn = (t + nslots < T) ? t + nslots : t;
; #pragma unroll
;           for (int i = 0; i < 16; ++i) en[i] = eidx[(size_t)tn * 128 + 8 * i]; }
;         __builtin_amdgcn_sched_barrier(0);
;         f32x2 acc2[8];
; #pragma unroll
;         for (int c = 0; c < 8; ++c) acc2[c] = (f32x2){0.f, 0.f};
; #pragma unroll
;         for (int i = 0; i < 16; ++i) { f32x2 vd[8]; fp8x16_dec2(vq[i], vd); const f32x2 c2 = {cf[i], cf[i]};
; #pragma unroll
;             for (int c = 0; c < 8; ++c) acc2[c] = __builtin_elementwise_fma(c2, vd[c], acc2[c]);
;             __builtin_amdgcn_sched_barrier(0); }
	v_pk_fma_f32 v[208:209], v[152:153], v[192:193], v[208:209] op_sel:[1,0,0] op_sel_hi:[1,1,1]
	v_cvt_pk_f32_fp8_e32 v[162:163], v104
	v_cvt_pk_f32_fp8_sdwa v[164:165], v104 src0_sel:WORD_1
	v_cvt_pk_f32_fp8_e32 v[166:167], v105
	v_cvt_pk_f32_fp8_sdwa v[168:169], v105 src0_sel:WORD_1
	v_cvt_pk_f32_fp8_e32 v[170:171], v106
	v_cvt_pk_f32_fp8_sdwa v[172:173], v106 src0_sel:WORD_1
	v_cvt_pk_f32_fp8_e32 v[174:175], v107
	v_cvt_pk_f32_fp8_sdwa v[176:177], v107 src0_sel:WORD_1
	v_lshl_add_u32 v230, v138, 7, v226
	global_load_dwordx4 v[104:107], v230, s[20:21]
	v_pk_fma_f32 v[194:195], v[154:155], v[162:163], v[194:195] op_sel_hi:[0,1,1]
	v_pk_fma_f32 v[196:197], v[154:155], v[164:165], v[196:197] op_sel_hi:[0,1,1]
	v_pk_fma_f32 v[198:199], v[154:155], v[166:167], v[198:199] op_sel_hi:[0,1,1]
	v_pk_fma_f32 v[200:201], v[154:155], v[168:169], v[200:201] op_sel_hi:[0,1,1]
	v_pk_fma_f32 v[202:203], v[154:155], v[170:171], v[202:203] op_sel_hi:[0,1,1]
	v_pk_fma_f32 v[204:205], v[154:155], v[172:173], v[204:205] op_sel_hi:[0,1,1]
	v_pk_fma_f32 v[206:207], v[154:155], v[174:175], v[206:207] op_sel_hi:[0,1,1]
	v_pk_fma_f32 v[208:209], v[154:155], v[176:177], v[208:209] op_sel_hi:[0,1,1]
	v_cvt_pk_f32_fp8_e32 v[178:179], v108
	v_cvt_pk_f32_fp8_sdwa v[180:181], v108 src0_sel:WORD_1
	v_cvt_pk_f32_fp8_e32 v[182:183], v109
	v_cvt_pk_f32_fp8_sdwa v[184:185], v109 src0_sel:WORD_1
	v_cvt_pk_f32_fp8_e32 v[186:187], v110
	v_cvt_pk_f32_fp8_sdwa v[188:189], v110 src0_sel:WORD_1
	v_cvt_pk_f32_fp8_e32 v[190:191], v111
	v_cvt_pk_f32_fp8_sdwa v[192:193], v111 src0_sel:WORD_1
	v_lshl_add_u32 v231, v139, 7, v226
	global_load_dwordx4 v[108:111], v231, s[20:21]
	v_pk_fma_f32 v[194:195], v[154:155], v[178:179], v[194:195] op_sel:[1,0,0] op_sel_hi:[1,1,1]
	v_pk_fma_f32 v[196:197], v[154:155], v[180:181], v[196:197] op_sel:[1,0,0] op_sel_hi:[1,1,1]
	v_pk_fma_f32 v[198:199], v[154:155], v[182:183], v[198:199] op_sel:[1,0,0] op_sel_hi:[1,1,1]
	v_pk_fma_f32 v[200:201], v[154:155], v[184:185], v[200:201] op_sel:[1,0,0] op_sel_hi:[1,1,1]
	v_pk_fma_f32 v[202:203], v[154:155], v[186:187], v[202:203] op_sel:[1,0,0] op_sel_hi:[1,1,1]
	v_pk_fma_f32 v[204:205], v[154:155], v[188:189], v[204:205] op_sel:[1,0,0] op_sel_hi:[1,1,1]
	v_pk_fma_f32 v[206:207], v[154:155], v[190:191], v[206:207] op_sel:[1,0,0] op_sel_hi:[1,1,1]
	v_pk_fma_f32 v[208:209], v[154:155], v[192:193], v[208:209] op_sel:[1,0,0] op_sel_hi:[1,1,1]
	v_cvt_pk_f32_fp8_e32 v[162:163], v112
	v_cvt_pk_f32_fp8_sdwa v[164:165], v112 src0_sel:WORD_1
	v_cvt_pk_f32_fp8_e32 v[166:167], v113
	v_cvt_pk_f32_fp8_sdwa v[168:169], v113 src0_sel:WORD_1
	v_cvt_pk_f32_fp8_e32 v[170:171], v114
	v_cvt_pk_f32_fp8_sdwa v[172:173], v114 src0_sel:WORD_1
	v_cvt_pk_f32_fp8_e32 v[174:175], v115
	v_cvt_pk_f32_fp8_sdwa v[176:177], v115 src0_sel:WORD_1
	v_lshl_add_u32 v230, v140, 7, v226
	global_load_dwordx4 v[112:115], v230, s[20:21]
	v_pk_fma_f32 v[194:195], v[156:157], v[162:163], v[194:195] op_sel_hi:[0,1,1]
	v_pk_fma_f32 v[196:197], v[156:157], v[164:165], v[196:197] op_sel_hi:[0,1,1]
	v_pk_fma_f32 v[198:199], v[156:157], v[166:167], v[198:199] op_sel_hi:[0,1,1]
	v_pk_fma_f32 v[200:201], v[156:157], v[168:169], v[200:201] op_sel_hi:[0,1,1]
	v_pk_fma_f32 v[202:203], v[156:157], v[170:171], v[202:203] op_sel_hi:[0,1,1]
	v_pk_fma_f32 v[204:205], v[156:157], v[172:173], v[204:205] op_sel_hi:[0,1,1]
	v_pk_fma_f32 v[206:207], v[156:157], v[174:175], v[206:207] op_sel_hi:[0,1,1]
	v_pk_fma_f32 v[208:209], v[156:157], v[176:177], v[208:209] op_sel_hi:[0,1,1]
	v_cvt_pk_f32_fp8_e32 v[178:179], v116
	v_cvt_pk_f32_fp8_sdwa v[180:181], v116 src0_sel:WORD_1
	v_cvt_pk_f32_fp8_e32 v[182:183], v117
	v_cvt_pk_f32_fp8_sdwa v[184:185], v117 src0_sel:WORD_1
	v_cvt_pk_f32_fp8_e32 v[186:187], v118
	v_cvt_pk_f32_fp8_sdwa v[188:189], v118 src0_sel:WORD_1
	v_cvt_pk_f32_fp8_e32 v[190:191], v119
	v_cvt_pk_f32_fp8_sdwa v[192:193], v119 src0_sel:WORD_1
	v_lshl_add_u32 v231, v141, 7, v226
	global_load_dwordx4 v[116:119], v231, s[20:21]
	v_pk_fma_f32 v[194:195], v[156:157], v[178:179], v[194:195] op_sel:[1,0,0] op_sel_hi:[1,1,1]
	v_pk_fma_f32 v[196:197], v[156:157], v[180:181], v[196:197] op_sel:[1,0,0] op_sel_hi:[1,1,1]
	v_pk_fma_f32 v[198:199], v[156:157], v[182:183], v[198:199] op_sel:[1,0,0] op_sel_hi:[1,1,1]
	v_pk_fma_f32 v[200:201], v[156:157], v[184:185], v[200:201] op_sel:[1,0,0] op_sel_hi:[1,1,1]
	v_pk_fma_f32 v[202:203], v[156:157], v[186:187], v[202:203] op_sel:[1,0,0] op_sel_hi:[1,1,1]
	v_pk_fma_f32 v[204:205], v[156:157], v[188:189], v[204:205] op_sel:[1,0,0] op_sel_hi:[1,1,1]
	v_pk_fma_f32 v[206:207], v[156:157], v[190:191], v[206:207] op_sel:[1,0,0] op_sel_hi:[1,1,1]
	v_pk_fma_f32 v[208:209], v[156:157], v[192:193], v[208:209] op_sel:[1,0,0] op_sel_hi:[1,1,1]
	v_cvt_pk_f32_fp8_e32 v[162:163], v120
	v_cvt_pk_f32_fp8_sdwa v[164:165], v120 src0_sel:WORD_1
	v_cvt_pk_f32_fp8_e32 v[166:167], v121
	v_cvt_pk_f32_fp8_sdwa v[168:169], v121 src0_sel:WORD_1
	v_cvt_pk_f32_fp8_e32 v[170:171], v122
	v_cvt_pk_f32_fp8_sdwa v[172:173], v122 src0_sel:WORD_1
	v_cvt_pk_f32_fp8_e32 v[174:175], v123
	v_cvt_pk_f32_fp8_sdwa v[176:177], v123 src0_sel:WORD_1
	v_lshl_add_u32 v230, v142, 7, v226
	global_load_dwordx4 v[120:123], v230, s[20:21]
	v_pk_fma_f32 v[194:195], v[158:159], v[162:163], v[194:195] op_sel_hi:[0,1,1]
	v_pk_fma_f32 v[196:197], v[158:159], v[164:165], v[196:197] op_sel_hi:[0,1,1]
	v_pk_fma_f32 v[198:199], v[158:159], v[166:167], v[198:199] op_sel_hi:[0,1,1]
	v_pk_fma_f32 v[200:201], v[158:159], v[168:169], v[200:201] op_sel_hi:[0,1,1]
	v_pk_fma_f32 v[202:203], v[158:159], v[170:171], v[202:203] op_sel_hi:[0,1,1]
	v_pk_fma_f32 v[204:205], v[158:159], v[172:173], v[204:205] op_sel_hi:[0,1,1]
; __device__ __forceinline__ unsigned cvt_pk_bf16(float lo, float hi) { const f32x2 v = {lo, hi}; return __builtin_bit_cast(unsigned, __builtin_convertvector(v, bf16x2v)); }
; template <int CTRL> __device__ __forceinline__ float dppf(float v) { return __builtin_bit_cast(float, __builtin_amdgcn_update_dpp(0, __builtin_bit_cast(int, v), CTRL, 0xF, 0xF, true)); }
; __device__ __forceinline__ void phase_peer_out(const Params& P, int l) {
;     ...
;         for (int i = 0; i < 16; ++i) { f32x2 vd[8]; fp8x16_dec2(vq[i], vd); const f32x2 c2 = {cf[i], cf[i]};
; #pragma unroll
;             for (int c = 0; c < 8; ++c) acc2[c] = __builtin_elementwise_fma(c2, vd[c], acc2[c]);
;             __builtin_amdgcn_sched_barrier(0); }
;         float acc[16];
; #pragma unroll
;         for (int c = 0; c < 8; ++c) { acc[2 * c] = acc2[c].x; acc[2 * c + 1] = acc2[c].y; }
; #pragma unroll
;         for (int c = 0; c < 16; ++c) acc[c] += dppf<0x128>(acc[c]);
;         float r8[8], r4[4];
;         { const bool up = (lane & 16) != 0;
; #pragma unroll
;           for (int c = 0; c < 8; ++c) { const float send = up ? acc[c] : acc[c + 8], keep = up ? acc[c + 8] : acc[c]; r8[c] = keep + __shfl_xor(send, 16); } }
;         { const bool up = (lane & 32) != 0;
; #pragma unroll
;           for (int c = 0; c < 4; ++c) { const float send = up ? r8[c] : r8[c + 4], keep = up ? r8[c + 4] : r8[c]; r4[c] = keep + __shfl_xor(send, 32); } }
;         if ((lane & 8) == 0) { u32x2 w; w.x = cvt_pk_bf16(DN_ALPHA * xo[0] + r4[0], DN_ALPHA * xo[1] + r4[1]); w.y = cvt_pk_bf16(DN_ALPHA * xo[2] + r4[2], DN_ALPHA * xo[3] + r4[3]);
;             *(u32x2*)((bf16_t*)(P.ws + WS_R0) + (yp - P.out)) = w; }
;     }
	v_pk_fma_f32 v[206:207], v[158:159], v[174:175], v[206:207] op_sel_hi:[0,1,1]
	v_pk_fma_f32 v[208:209], v[158:159], v[176:177], v[208:209] op_sel_hi:[0,1,1]
	v_cvt_pk_f32_fp8_e32 v[178:179], v124
	v_cvt_pk_f32_fp8_sdwa v[180:181], v124 src0_sel:WORD_1
	v_cvt_pk_f32_fp8_e32 v[182:183], v125
	v_cvt_pk_f32_fp8_sdwa v[184:185], v125 src0_sel:WORD_1
	v_cvt_pk_f32_fp8_e32 v[186:187], v126
	v_cvt_pk_f32_fp8_sdwa v[188:189], v126 src0_sel:WORD_1
	v_cvt_pk_f32_fp8_e32 v[190:191], v127
	v_cvt_pk_f32_fp8_sdwa v[192:193], v127 src0_sel:WORD_1
	v_lshl_add_u32 v231, v143, 7, v226
	global_load_dwordx4 v[124:127], v231, s[20:21]
	v_pk_fma_f32 v[194:195], v[158:159], v[178:179], v[194:195] op_sel:[1,0,0] op_sel_hi:[1,1,1]
	v_pk_fma_f32 v[196:197], v[158:159], v[180:181], v[196:197] op_sel:[1,0,0] op_sel_hi:[1,1,1]
	v_pk_fma_f32 v[198:199], v[158:159], v[182:183], v[198:199] op_sel:[1,0,0] op_sel_hi:[1,1,1]
	v_pk_fma_f32 v[200:201], v[158:159], v[184:185], v[200:201] op_sel:[1,0,0] op_sel_hi:[1,1,1]
	v_pk_fma_f32 v[202:203], v[158:159], v[186:187], v[202:203] op_sel:[1,0,0] op_sel_hi:[1,1,1]
	v_pk_fma_f32 v[204:205], v[158:159], v[188:189], v[204:205] op_sel:[1,0,0] op_sel_hi:[1,1,1]
	v_pk_fma_f32 v[206:207], v[158:159], v[190:191], v[206:207] op_sel:[1,0,0] op_sel_hi:[1,1,1]
	v_pk_fma_f32 v[208:209], v[158:159], v[192:193], v[208:209] op_sel:[1,0,0] op_sel_hi:[1,1,1]
	s_nop 1
	v_add_f32_dpp v194, v194, v194 row_ror:8 row_mask:0xf bank_mask:0xf bound_ctrl:1
	v_add_f32_dpp v195, v195, v195 row_ror:8 row_mask:0xf bank_mask:0xf bound_ctrl:1
	v_add_f32_dpp v196, v196, v196 row_ror:8 row_mask:0xf bank_mask:0xf bound_ctrl:1
	v_add_f32_dpp v197, v197, v197 row_ror:8 row_mask:0xf bank_mask:0xf bound_ctrl:1
	v_add_f32_dpp v198, v198, v198 row_ror:8 row_mask:0xf bank_mask:0xf bound_ctrl:1
	v_add_f32_dpp v199, v199, v199 row_ror:8 row_mask:0xf bank_mask:0xf bound_ctrl:1
	v_add_f32_dpp v200, v200, v200 row_ror:8 row_mask:0xf bank_mask:0xf bound_ctrl:1
	v_add_f32_dpp v201, v201, v201 row_ror:8 row_mask:0xf bank_mask:0xf bound_ctrl:1
	v_add_f32_dpp v202, v202, v202 row_ror:8 row_mask:0xf bank_mask:0xf bound_ctrl:1
	v_add_f32_dpp v203, v203, v203 row_ror:8 row_mask:0xf bank_mask:0xf bound_ctrl:1
	v_add_f32_dpp v204, v204, v204 row_ror:8 row_mask:0xf bank_mask:0xf bound_ctrl:1
	v_add_f32_dpp v205, v205, v205 row_ror:8 row_mask:0xf bank_mask:0xf bound_ctrl:1
	v_add_f32_dpp v206, v206, v206 row_ror:8 row_mask:0xf bank_mask:0xf bound_ctrl:1
	v_add_f32_dpp v207, v207, v207 row_ror:8 row_mask:0xf bank_mask:0xf bound_ctrl:1
	v_add_f32_dpp v208, v208, v208 row_ror:8 row_mask:0xf bank_mask:0xf bound_ctrl:1
	v_add_f32_dpp v209, v209, v209 row_ror:8 row_mask:0xf bank_mask:0xf bound_ctrl:1
	s_nop 1
	v_permlane16_swap_b32 v194, v202
	v_permlane16_swap_b32 v195, v203
	v_permlane16_swap_b32 v196, v204
	v_permlane16_swap_b32 v197, v205
	v_permlane16_swap_b32 v198, v206
	v_permlane16_swap_b32 v199, v207
	v_permlane16_swap_b32 v200, v208
	v_permlane16_swap_b32 v201, v209
	v_add_f32_e32 v194, v194, v202
	v_add_f32_e32 v195, v195, v203
	v_add_f32_e32 v196, v196, v204
	v_add_f32_e32 v197, v197, v205
	v_add_f32_e32 v198, v198, v206
	v_add_f32_e32 v199, v199, v207
	v_add_f32_e32 v200, v200, v208
	v_add_f32_e32 v201, v201, v209
	s_nop 1
	v_permlane32_swap_b32 v194, v198
	v_permlane32_swap_b32 v195, v199
	v_permlane32_swap_b32 v196, v200
	v_permlane32_swap_b32 v197, v201
	v_add_f32_e32 v194, v194, v198
	v_add_f32_e32 v195, v195, v199
	v_add_f32_e32 v196, v196, v200
	v_add_f32_e32 v197, v197, v201
	v_fma_f32 v194, v214, s10, v194
	v_fma_f32 v195, v215, s10, v195
	v_fma_f32 v196, v216, s10, v196
	v_fma_f32 v197, v217, s10, v197
	v_cvt_pk_bf16_f32 v236, v194, v195
	v_cvt_pk_bf16_f32 v237, v196, v197
	s_add_u32 s29, s28, 1
	s_min_u32 s29, s29, 0x7f
	s_lshl_b32 s29, s29, 19
	s_add_u32 s30, s6, s29
	s_addc_u32 s31, s7, 0
	s_mov_b64 exec, s[8:9]
	global_store_dwordx2 v228, v[236:237], s[30:31]
	s_mov_b64 exec, -1
	s_add_u32 s28, s28, 2
	s_cmpk_lt_u32 s28, 0x80
	s_cbranch_scc1 .Lpout_loop_L0
	s_waitcnt vmcnt(0)
	s_branch .Lseam_ph12
; __device__ __forceinline__ void phase_peer_out(const Params& P, int l) {
;     const int lane = threadIdx.x & 63, sub = lane & 7, grp = lane >> 3;
;     const int s = blockIdx.x & 7, nslots = (gridDim.x >> 3) * 8, wslot = (blockIdx.x >> 3) * 8 + (threadIdx.x >> 6);
;     const unsigned char* PV = P.ws + WS_PT + (size_t)(2 * l + 1) * NEXP * DM + (size_t)s * NEXP * 128;
;     const unsigned lo = 16u * (unsigned)sub;
;     const int* eidx = (const int*)(P.ws + WS_R5) + grp; const float* cfp = (const float*)(P.ws + WS_CF) + grp;
;     if ((int)(blockIdx.x >> 3) * 8 >= nslots) return;
;     int en[16];
; #pragma unroll
;     for (int i = 0; i < 16; ++i) en[i] = eidx[(size_t)wslot * 128 + 8 * i];
.Lpout_orig_L0:
	s_load_dword s0, s[96:97], 0xd0
	s_add_u32 s10, s96, 0xd0
	s_addc_u32 s11, s97, 0
	s_and_b32 s1, s2, -8
	v_add_u32_e32 v32, s1, v240
	s_waitcnt lgkmcnt(0)
	s_and_b32 s12, s0, -8
	s_cmp_lt_i32 s1, s12
	s_mov_b32 s1, 0x8000
	s_cselect_b64 s[4:5], -1, 0
	v_cmp_gt_i32_e32 vcc, s1, v32
	s_and_b64 s[4:5], vcc, s[4:5]
	s_and_saveexec_b64 s[14:15], s[4:5]
	s_cbranch_execz .LBB0_1033
	v_lshrrev_b32_e32 v6, 1, v160
	v_and_b32_e32 v0, 28, v6
	v_mov_b32_e32 v1, 0
	v_lshl_add_u64 v[2:3], s[86:87], 0, v[0:1]
	s_mov_b64 s[4:5], 0x18000000
	v_ashrrev_i32_e32 v33, 31, v32
	v_lshl_add_u64 v[34:35], v[2:3], 0, s[4:5]
	v_lshlrev_b64 v[2:3], 9, v[32:33]
	v_lshl_add_u64 v[4:5], v[34:35], 0, v[2:3]
	global_load_dword v47, v[4:5], off offset:480
	global_load_dword v51, v[4:5], off offset:448
	global_load_dword v53, v[4:5], off offset:416
	global_load_dword v55, v[4:5], off offset:384
	global_load_dword v57, v[4:5], off offset:352
	global_load_dword v58, v[4:5], off offset:320
	global_load_dword v59, v[4:5], off offset:288
	global_load_dword v60, v[4:5], off offset:256
	global_load_dword v61, v[4:5], off offset:224
	global_load_dword v62, v[4:5], off offset:192
	global_load_dword v63, v[4:5], off offset:160
	global_load_dword v64, v[4:5], off offset:128
	global_load_dword v65, v[4:5], off offset:96
	global_load_dword v66, v[4:5], off offset:64
	global_load_dword v67, v[4:5], off offset:32
	global_load_dword v68, v[4:5], off
	s_and_b32 s3, s2, 7
	v_mbcnt_lo_u32_b32 v5, -1, 0
	s_lshl_b32 s4, s3, 21
	v_mbcnt_hi_u32_b32 v5, -1, v5
	s_add_u32 s4, s86, s4
	v_and_b32_e32 v8, 64, v5
	s_addc_u32 s5, s87, 0
	v_xor_b32_e32 v7, 16, v5
	v_add_u32_e32 v8, 64, v8
	s_add_u32 s16, s4, 0x1d000000
	v_lshlrev_b32_e32 v1, 4, v160
	v_cmp_lt_i32_e64 s[6:7], v7, v8
	s_addc_u32 s17, s5, 0
	v_and_b32_e32 v37, 0x70, v1
	v_and_b32_e32 v1, 16, v160
	v_and_b32_e32 v4, 32, v160
	v_cndmask_b32_e64 v7, v5, v7, s[6:7]
	v_cmp_eq_u32_e32 vcc, 0, v1
	v_lshrrev_b32_e32 v1, 1, v1
	v_cmp_eq_u32_e64 s[4:5], 0, v4
	v_lshrrev_b32_e32 v4, 3, v4
	v_lshlrev_b32_e32 v45, 2, v7
	v_xor_b32_e32 v7, 32, v5
	s_add_u32 s18, s86, 0x4000000
	v_cmp_lt_i32_e64 s[6:7], v7, v8
	s_addc_u32 s19, s87, 0
	v_or3_b32 v1, v1, v4, v37
	s_lshl_b32 s3, s3, 9
	v_cndmask_b32_e64 v5, v5, v7, s[6:7]
	v_lshl_or_b32 v36, v1, 2, s3
	v_and_b32_e32 v1, 7, v160
	v_lshlrev_b32_e32 v49, 2, v5
	v_and_b32_e32 v5, 8, v160
	v_lshlrev_b64 v[38:39], 12, v[32:33]
	v_lshlrev_b32_e32 v1, 6, v1
	v_lshlrev_b32_e32 v4, 1, v160
	v_cmp_eq_u32_e64 s[6:7], 0, v5
	v_or3_b32 v1, v38, s3, v1
	v_and_b32_e32 v4, 32, v4
	v_and_b32_e32 v5, 16, v6
	v_or_b32_e32 v2, v2, v0
	v_or3_b32 v4, v1, v4, v5
	v_mov_b32_e32 v5, v39
	s_ashr_i32 s13, s12, 31
	v_lshl_add_u64 v[0:1], s[86:87], 0, v[2:3]
	s_mov_b64 s[8:9], 0x10000000
	v_lshl_add_u64 v[40:41], s[84:85], 0, v[4:5]
	s_lshl_b64 s[20:21], s[12:13], 12
	v_lshl_add_u64 v[42:43], v[0:1], 0, s[8:9]
	s_lshl_b64 s[22:23], s[12:13], 9
	s_mov_b64 s[24:25], 0
	s_movk_i32 s3, 0x7fff
	s_mov_b32 s26, 0x3fb504f3
	s_mov_b64 s[28:29], 0
	s_branch .LBB0_1031

; __device__ __forceinline__ unsigned xb_add(unsigned* p, unsigned v) { return __hip_atomic_fetch_add(p, v, __ATOMIC_RELAXED, __HIP_MEMORY_SCOPE_AGENT); }
; __device__ __forceinline__ void xcd_barrier(const XcdBarrier& b) {
;     asm volatile("s_waitcnt vmcnt(0)" ::: "memory");
;     __syncthreads();
;     if (threadIdx.x == 0) {
;         unsigned* bar = b.bar;
;         __builtin_amdgcn_s_waitcnt(0);
;         unsigned nloc = b.st[0], nx = b.st[1];
;         if (nloc == 0u) { xcd_barrier_complete(bar, b.x, nloc, nx); b.st[0] = nloc; b.st[1] = nx; }
;         const unsigned old = xb_add(&bar[XB_XSUB(b.x)], 1u);
;         const unsigned gen = old / nloc;
;         if (old + 1u == (gen + 1u) * nloc) {
.Lseam_ph12:
	s_cmp_gt_i32 s93, 13
	s_cselect_b64 s[4:5], -1, 0
	s_cmp_lg_u32 s94, 0
	s_cselect_b64 s[6:7], -1, 0
	s_and_b64 s[4:5], s[4:5], s[6:7]
	s_andn2_b64 vcc, exec, s[4:5]
	s_cbranch_vccnz .LBB0_1083
	s_waitcnt vmcnt(0)
	s_waitcnt vmcnt(0) lgkmcnt(0)
	s_barrier
	s_and_saveexec_b64 s[4:5], s[90:91]
	s_cbranch_execz .LBB0_1082
	s_add_i32 s1, 0, 0x20080
	v_mov_b32_e32 v0, s1
	s_waitcnt vmcnt(0) expcnt(0) lgkmcnt(0)
	ds_read_b32 v2, v0
	s_add_i32 s1, 0, 0x20084
	v_mov_b32_e32 v0, s1
	ds_read_b32 v0, v0
	s_waitcnt lgkmcnt(1)
	v_cmp_ne_u32_e32 vcc, 0, v2
	s_cbranch_vccnz .LBB0_1050
	s_add_u32 s6, s86, 0x1000
	s_load_dwordx2 s[12:13], s[10:11], 0x4
	s_addc_u32 s7, s87, 0
	s_add_u32 s8, s86, 0x1100
	s_addc_u32 s9, s87, 0
	s_add_u32 s10, s86, 0x1200
	s_addc_u32 s11, s87, 0
	s_waitcnt lgkmcnt(0)
	s_mul_i32 s0, s12, s0
	s_add_u32 s12, s86, 0x1300
	s_mul_i32 s0, s0, s13
	s_addc_u32 s13, s87, 0
	s_mov_b32 s1, 1
	v_mov_b32_e32 v16, 0
	s_branch .LBB0_1038

; __device__ __forceinline__ unsigned xb_add(unsigned* p, unsigned v) { return __hip_atomic_fetch_add(p, v, __ATOMIC_RELAXED, __HIP_MEMORY_SCOPE_AGENT); }
; __device__ __forceinline__ void xcd_barrier(const XcdBarrier& b) {
;     asm volatile("s_waitcnt vmcnt(0)" ::: "memory");
;     __syncthreads();
;     if (threadIdx.x == 0) {
;         unsigned* bar = b.bar;
;         __builtin_amdgcn_s_waitcnt(0);
;         unsigned nloc = b.st[0], nx = b.st[1];
;         if (nloc == 0u) { xcd_barrier_complete(bar, b.x, nloc, nx); b.st[0] = nloc; b.st[1] = nx; }
;         const unsigned old = xb_add(&bar[XB_XSUB(b.x)], 1u);
;         const unsigned gen = old / nloc;
;         if (old + 1u == (gen + 1u) * nloc) {
.LBB0_1989:
.Lseam_ph23:
	s_cmp_gt_i32 s93, 24
	s_cselect_b64 s[4:5], -1, 0
	s_cmp_lg_u32 s94, 0
	s_cselect_b64 s[6:7], -1, 0
	s_and_b64 s[4:5], s[4:5], s[6:7]
	s_andn2_b64 vcc, exec, s[4:5]
	s_cbranch_vccnz .LBB0_2039
	s_waitcnt vmcnt(0)
	s_waitcnt vmcnt(0)
	s_barrier
	s_and_saveexec_b64 s[4:5], s[90:91]
	s_cbranch_execz .LBB0_2038
	s_add_i32 s1, 0, 0x20080
	v_mov_b32_e32 v0, s1
	s_waitcnt vmcnt(0) expcnt(0) lgkmcnt(0)
	ds_read_b32 v2, v0
	s_add_i32 s1, 0, 0x20084
	v_mov_b32_e32 v0, s1
	ds_read_b32 v0, v0
	s_waitcnt lgkmcnt(1)
	v_cmp_ne_u32_e32 vcc, 0, v2
	s_cbranch_vccnz .LBB0_2006
	s_load_dwordx2 s[10:11], s[22:23], 0x4
	s_add_u32 s6, s86, 0x1000
	s_addc_u32 s7, s87, 0
	s_add_u32 s8, s86, 0x1100
	s_addc_u32 s9, s87, 0
	s_waitcnt lgkmcnt(0)
	s_mul_i32 s0, s10, s0
	s_add_u32 s10, s86, 0x1200
	s_mul_i32 s0, s0, s11
	s_addc_u32 s11, s87, 0
	s_add_u32 s12, s86, 0x1300
	s_addc_u32 s13, s87, 0
	s_mov_b32 s1, 1
	v_mov_b32_e32 v16, 0
	s_branch .LBB0_1994

; __device__ __forceinline__ void phase_peer_out(const Params& P, int l) {
;     const int lane = threadIdx.x & 63, sub = lane & 7, grp = lane >> 3;
;     const int s = blockIdx.x & 7, nslots = (gridDim.x >> 3) * 8, wslot = (blockIdx.x >> 3) * 8 + (threadIdx.x >> 6);
;     const unsigned char* PV = P.ws + WS_PT + (size_t)(2 * l + 1) * NEXP * DM + (size_t)s * NEXP * 128;
;     const unsigned lo = 16u * (unsigned)sub;
;     const int* eidx = (const int*)(P.ws + WS_R5) + grp; const float* cfp = (const float*)(P.ws + WS_CF) + grp;
;     if ((int)(blockIdx.x >> 3) * 8 >= nslots) return;
;     int en[16];
; #pragma unroll
;     for (int i = 0; i < 16; ++i) en[i] = eidx[(size_t)wslot * 128 + 8 * i];
;     for (int t = wslot; t < T; t += nslots) {
;         u32x4 vq[16]; float cf[16];
; #pragma unroll
;         for (int i = 0; i < 16; ++i) { vq[i] = *(const u32x4*)(PV + ((unsigned)en[i] * 128u + lo)); cf[i] = cfp[(size_t)t * 128 + 8 * i]; }
;         float* yp = P.out + (size_t)t * DM + 128 * s + 16 * sub + ((lane & 16) ? 8 : 0) + ((lane & 32) ? 4 : 0);
;         const f32x4 xo = *(const f32x4*)yp;
;         { const int tn = (t + nslots < T) ? t + nslots : t;
; #pragma unroll
;           for (int i = 0; i < 16; ++i) en[i] = eidx[(size_t)tn * 128 + 8 * i]; }
.LBB0_2093:
	s_cmp_lt_i32 s92, 26
	s_cselect_b64 s[0:1], -1, 0
	s_cmp_gt_i32 s93, 25
	s_cselect_b64 s[4:5], -1, 0
	s_and_b64 s[0:1], s[0:1], s[4:5]
	s_andn2_b64 vcc, exec, s[0:1]
	s_cbranch_vccnz .LBB0_2149
	s_load_dword s0, s[96:97], 0xd0
	s_waitcnt lgkmcnt(0)
	s_cmpk_lg_u32 s0, 0x100
	s_cbranch_scc1 .Lpout_orig_L1
	s_mov_b64 exec, -1
	v_and_b32_e32 v234, 63, v160
	v_and_b32_e32 v226, 7, v160
	v_bfe_u32 v235, v160, 3, 3
	v_lshrrev_b32_e32 v230, 6, v160
	v_lshlrev_b32_e32 v227, 3, v234
	v_readfirstlane_b32 s0, v230
	v_lshlrev_b32_e32 v230, 10, v230
	v_lshl_add_u32 v233, v235, 6, v230
	v_and_b32_e32 v231, 3, v234
	v_lshl_add_u32 v232, v231, 7, v230
	v_lshrrev_b32_e32 v231, 2, v234
	v_lshl_add_u32 v232, v231, 2, v232
	v_bfe_u32 v230, v234, 4, 1
	v_lshrrev_b32_e32 v231, 5, v234
	v_lshlrev_b32_e32 v228, 5, v226
	v_lshl_add_u32 v228, v230, 4, v228
	v_lshl_add_u32 v228, v231, 3, v228
	v_lshlrev_b32_e32 v229, 1, v228
	v_lshlrev_b32_e32 v226, 4, v226
	s_nop 3
	s_and_b32 s1, s2, 7
	s_and_b32 s3, s2, -8
	s_add_u32 s3, s3, s0
	s_lshl_b32 s28, s1, 21
	s_add_u32 s20, s86, s28
	s_addc_u32 s21, s87, 0
	s_add_u32 s20, s20, 0x1f000000
	s_addc_u32 s21, s21, 0
	s_lshl_b32 s28, s3, 9
	s_add_u32 s22, s86, s28
	s_addc_u32 s23, s87, 0
	s_add_u32 s24, s22, 0x10000000
	s_addc_u32 s25, s23, 0
	s_add_u32 s22, s22, 0x18000000
	s_addc_u32 s23, s23, 0
	s_lshl_b32 s28, s3, 12
	s_lshl_b32 s29, s1, 9
	s_add_u32 s28, s28, s29
	s_add_u32 s4, s84, s28
	s_addc_u32 s5, s85, 0
	s_lshr_b32 s28, s28, 1
	s_add_u32 s6, s86, s28
	s_addc_u32 s7, s87, 0
	s_add_u32 s6, s6, 0x4000000
	s_addc_u32 s7, s7, 0
	s_mov_b32 s8, 0xff00ff
	s_mov_b32 s9, 0xff00ff
	s_mov_b32 s10, 0x3fb504f3
	s_mov_b32 s30, s22
	s_mov_b32 s31, s23
	global_load_dwordx2 v[218:219], v227, s[30:31]
	s_waitcnt vmcnt(0)
	ds_write2_b32 v232, v218, v219 offset1:16
	ds_read_b128 v[128:131], v233
	ds_read_b128 v[132:135], v233 offset:16
	ds_read_b128 v[136:139], v233 offset:32
	ds_read_b128 v[140:143], v233 offset:48
	s_waitcnt lgkmcnt(0)
	v_lshl_add_u32 v230, v128, 7, v226
	global_load_dwordx4 v[0:3], v230, s[20:21]
	v_lshl_add_u32 v231, v129, 7, v226
	global_load_dwordx4 v[4:7], v231, s[20:21]
	v_lshl_add_u32 v230, v130, 7, v226
	global_load_dwordx4 v[8:11], v230, s[20:21]
	v_lshl_add_u32 v231, v131, 7, v226
	global_load_dwordx4 v[12:15], v231, s[20:21]
	v_lshl_add_u32 v230, v132, 7, v226
	global_load_dwordx4 v[16:19], v230, s[20:21]
	v_lshl_add_u32 v231, v133, 7, v226
	global_load_dwordx4 v[20:23], v231, s[20:21]
	v_lshl_add_u32 v230, v134, 7, v226
	global_load_dwordx4 v[24:27], v230, s[20:21]
	v_lshl_add_u32 v231, v135, 7, v226
	global_load_dwordx4 v[28:31], v231, s[20:21]
	v_lshl_add_u32 v230, v136, 7, v226
	global_load_dwordx4 v[32:35], v230, s[20:21]
	v_lshl_add_u32 v231, v137, 7, v226
	global_load_dwordx4 v[36:39], v231, s[20:21]
	v_lshl_add_u32 v230, v138, 7, v226
	global_load_dwordx4 v[40:43], v230, s[20:21]
	v_lshl_add_u32 v231, v139, 7, v226
	global_load_dwordx4 v[44:47], v231, s[20:21]
	v_lshl_add_u32 v230, v140, 7, v226
	global_load_dwordx4 v[48:51], v230, s[20:21]
	v_lshl_add_u32 v231, v141, 7, v226
	global_load_dwordx4 v[52:55], v231, s[20:21]
	v_lshl_add_u32 v230, v142, 7, v226
	global_load_dwordx4 v[56:59], v230, s[20:21]
	v_lshl_add_u32 v231, v143, 7, v226
	global_load_dwordx4 v[60:63], v231, s[20:21]
	s_add_u32 s30, s22, 0x20000
	s_addc_u32 s31, s23, 0
	global_load_dwordx2 v[218:219], v227, s[30:31]
	s_waitcnt vmcnt(0)
	ds_write2_b32 v232, v218, v219 offset1:16
	ds_read_b128 v[128:131], v233
	ds_read_b128 v[132:135], v233 offset:16
	ds_read_b128 v[136:139], v233 offset:32
	ds_read_b128 v[140:143], v233 offset:48
	s_waitcnt lgkmcnt(0)
	v_lshl_add_u32 v230, v128, 7, v226
	global_load_dwordx4 v[64:67], v230, s[20:21]
	v_lshl_add_u32 v231, v129, 7, v226
	global_load_dwordx4 v[68:71], v231, s[20:21]
	v_lshl_add_u32 v230, v130, 7, v226
	global_load_dwordx4 v[72:75], v230, s[20:21]
	v_lshl_add_u32 v231, v131, 7, v226
	global_load_dwordx4 v[76:79], v231, s[20:21]
	v_lshl_add_u32 v230, v132, 7, v226
	global_load_dwordx4 v[80:83], v230, s[20:21]
	v_lshl_add_u32 v231, v133, 7, v226
	global_load_dwordx4 v[84:87], v231, s[20:21]
	v_lshl_add_u32 v230, v134, 7, v226
	global_load_dwordx4 v[88:91], v230, s[20:21]
	v_lshl_add_u32 v231, v135, 7, v226
	global_load_dwordx4 v[92:95], v231, s[20:21]
	v_lshl_add_u32 v230, v136, 7, v226
	global_load_dwordx4 v[96:99], v230, s[20:21]
	v_lshl_add_u32 v231, v137, 7, v226
	global_load_dwordx4 v[100:103], v231, s[20:21]
	v_lshl_add_u32 v230, v138, 7, v226
	global_load_dwordx4 v[104:107], v230, s[20:21]
	v_lshl_add_u32 v231, v139, 7, v226
	global_load_dwordx4 v[108:111], v231, s[20:21]
	v_lshl_add_u32 v230, v140, 7, v226
	global_load_dwordx4 v[112:115], v230, s[20:21]
	v_lshl_add_u32 v231, v141, 7, v226
	global_load_dwordx4 v[116:119], v231, s[20:21]
	v_lshl_add_u32 v230, v142, 7, v226
	global_load_dwordx4 v[120:123], v230, s[20:21]
	v_lshl_add_u32 v231, v143, 7, v226
	global_load_dwordx4 v[124:127], v231, s[20:21]
	s_add_u32 s30, s22, 0x40000
	s_addc_u32 s31, s23, 0
	global_load_dwordx2 v[220:221], v227, s[30:31]
	s_mov_b32 s30, s24
	s_mov_b32 s31, s25
	global_load_dwordx2 v[224:225], v227, s[30:31]
	s_mov_b32 s30, s4
	s_mov_b32 s31, s5
	global_load_dwordx4 v[210:213], v229, s[30:31]
	s_waitcnt vmcnt(0)
	s_mov_b32 s28, 0

; __device__ __forceinline__ void phase_peer_out(const Params& P, int l) {
;     const int lane = threadIdx.x & 63, sub = lane & 7, grp = lane >> 3;
;     const int s = blockIdx.x & 7, nslots = (gridDim.x >> 3) * 8, wslot = (blockIdx.x >> 3) * 8 + (threadIdx.x >> 6);
;     const unsigned char* PV = P.ws + WS_PT + (size_t)(2 * l + 1) * NEXP * DM + (size_t)s * NEXP * 128;
;     const unsigned lo = 16u * (unsigned)sub;
;     const int* eidx = (const int*)(P.ws + WS_R5) + grp; const float* cfp = (const float*)(P.ws + WS_CF) + grp;
;     if ((int)(blockIdx.x >> 3) * 8 >= nslots) return;
;     int en[16];
; #pragma unroll
;     for (int i = 0; i < 16; ++i) en[i] = eidx[(size_t)wslot * 128 + 8 * i];
.Lpout_orig_L1:
	s_load_dword s0, s[96:97], 0xd0
	s_add_u32 s10, s96, 0xd0
	s_addc_u32 s11, s97, 0
	s_and_b32 s1, s2, -8
	v_add_u32_e32 v36, s1, v240
	s_waitcnt lgkmcnt(0)
	s_and_b32 s12, s0, -8
	s_cmp_lt_i32 s1, s12
	s_mov_b32 s1, 0x8000
	s_cselect_b64 s[4:5], -1, 0
	v_cmp_gt_i32_e32 vcc, s1, v36
	s_and_b64 s[4:5], vcc, s[4:5]
	s_and_saveexec_b64 s[14:15], s[4:5]
	s_cbranch_execz .LBB0_2099
	v_lshrrev_b32_e32 v6, 1, v160
	v_and_b32_e32 v0, 28, v6
	v_mov_b32_e32 v1, 0
	v_lshl_add_u64 v[2:3], s[86:87], 0, v[0:1]
	s_mov_b64 s[4:5], 0x18000000
	v_ashrrev_i32_e32 v37, 31, v36
	v_lshl_add_u64 v[38:39], v[2:3], 0, s[4:5]
	v_lshlrev_b64 v[2:3], 9, v[36:37]
	v_lshl_add_u64 v[4:5], v[38:39], 0, v[2:3]
	global_load_dword v51, v[4:5], off offset:480
	global_load_dword v55, v[4:5], off offset:448
	global_load_dword v57, v[4:5], off offset:416
	global_load_dword v59, v[4:5], off offset:384
	global_load_dword v61, v[4:5], off offset:352
	global_load_dword v62, v[4:5], off offset:320
	global_load_dword v63, v[4:5], off offset:288
	global_load_dword v64, v[4:5], off offset:256
	global_load_dword v65, v[4:5], off offset:224
	global_load_dword v66, v[4:5], off offset:192
	global_load_dword v67, v[4:5], off offset:160
	global_load_dword v68, v[4:5], off offset:128
	global_load_dword v69, v[4:5], off offset:96
	global_load_dword v70, v[4:5], off offset:64
	global_load_dword v71, v[4:5], off offset:32
	global_load_dword v72, v[4:5], off
	s_and_b32 s3, s2, 7
	v_mbcnt_lo_u32_b32 v5, -1, 0
	s_lshl_b32 s4, s3, 21
	v_mbcnt_hi_u32_b32 v5, -1, v5
	s_add_u32 s4, s86, s4
	v_and_b32_e32 v8, 64, v5
	s_addc_u32 s5, s87, 0
	v_xor_b32_e32 v7, 16, v5
	v_add_u32_e32 v8, 64, v8
	s_add_u32 s16, s4, 0x1f000000
	v_lshlrev_b32_e32 v1, 4, v160
	v_cmp_lt_i32_e64 s[6:7], v7, v8
	s_addc_u32 s17, s5, 0
	v_and_b32_e32 v41, 0x70, v1
	v_and_b32_e32 v1, 16, v160
	v_and_b32_e32 v4, 32, v160
	v_cndmask_b32_e64 v7, v5, v7, s[6:7]
	v_cmp_eq_u32_e32 vcc, 0, v1
	v_lshrrev_b32_e32 v1, 1, v1
	v_cmp_eq_u32_e64 s[4:5], 0, v4
	v_lshrrev_b32_e32 v4, 3, v4
	v_lshlrev_b32_e32 v49, 2, v7
	v_xor_b32_e32 v7, 32, v5
	s_add_u32 s18, s86, 0x4000000
	v_cmp_lt_i32_e64 s[6:7], v7, v8
	s_addc_u32 s19, s87, 0
	v_or3_b32 v1, v1, v4, v41
	s_lshl_b32 s3, s3, 9
	v_cndmask_b32_e64 v5, v5, v7, s[6:7]
	v_lshl_or_b32 v40, v1, 2, s3
	v_and_b32_e32 v1, 7, v160
	v_lshlrev_b32_e32 v53, 2, v5
	v_and_b32_e32 v5, 8, v160
	v_lshlrev_b64 v[42:43], 12, v[36:37]
	v_lshlrev_b32_e32 v1, 6, v1
	v_lshlrev_b32_e32 v4, 1, v160
	v_cmp_eq_u32_e64 s[6:7], 0, v5
	v_or3_b32 v1, v42, s3, v1
	v_and_b32_e32 v4, 32, v4
	v_and_b32_e32 v5, 16, v6
	v_or_b32_e32 v2, v2, v0
	v_or3_b32 v4, v1, v4, v5
	v_mov_b32_e32 v5, v43
	s_ashr_i32 s13, s12, 31
	v_lshl_add_u64 v[0:1], s[86:87], 0, v[2:3]
	s_mov_b64 s[8:9], 0x10000000
	v_lshl_add_u64 v[44:45], s[84:85], 0, v[4:5]
	s_lshl_b64 s[20:21], s[12:13], 12
	v_lshl_add_u64 v[46:47], v[0:1], 0, s[8:9]
	s_lshl_b64 s[22:23], s[12:13], 9
	s_mov_b64 s[24:25], 0
	s_movk_i32 s3, 0x7fff
	s_mov_b32 s26, 0x3fb504f3
	s_mov_b64 s[28:29], 0
	s_branch .LBB0_2097

; __device__ __forceinline__ unsigned xb_add(unsigned* p, unsigned v) { return __hip_atomic_fetch_add(p, v, __ATOMIC_RELAXED, __HIP_MEMORY_SCOPE_AGENT); }
; __device__ __forceinline__ void xcd_barrier(const XcdBarrier& b) {
;     asm volatile("s_waitcnt vmcnt(0)" ::: "memory");
;     __syncthreads();
;     if (threadIdx.x == 0) {
;         unsigned* bar = b.bar;
;         __builtin_amdgcn_s_waitcnt(0);
;         unsigned nloc = b.st[0], nx = b.st[1];
;         if (nloc == 0u) { xcd_barrier_complete(bar, b.x, nloc, nx); b.st[0] = nloc; b.st[1] = nx; }
;         const unsigned old = xb_add(&bar[XB_XSUB(b.x)], 1u);
;         const unsigned gen = old / nloc;
;         if (old + 1u == (gen + 1u) * nloc) {
.Lseam_ph25:
	s_cmp_gt_i32 s93, 26
	s_cselect_b64 s[4:5], -1, 0
	s_cmp_lg_u32 s94, 0
	s_cselect_b64 s[6:7], -1, 0
	s_and_b64 s[4:5], s[4:5], s[6:7]
	s_andn2_b64 vcc, exec, s[4:5]
	s_cbranch_vccnz .LBB0_2149
	s_waitcnt vmcnt(0)
	s_waitcnt vmcnt(0) lgkmcnt(0)
	s_barrier
	s_and_saveexec_b64 s[4:5], s[90:91]
	s_cbranch_execz .LBB0_2148
	s_add_i32 s1, 0, 0x20080
	v_mov_b32_e32 v0, s1
	s_waitcnt vmcnt(0) expcnt(0) lgkmcnt(0)
	ds_read_b32 v2, v0
	s_add_i32 s1, 0, 0x20084
	v_mov_b32_e32 v0, s1
	ds_read_b32 v0, v0
	s_waitcnt lgkmcnt(1)
	v_cmp_ne_u32_e32 vcc, 0, v2
	s_cbranch_vccnz .LBB0_2116
	s_add_u32 s6, s86, 0x1000
	s_load_dwordx2 s[12:13], s[10:11], 0x4
	s_addc_u32 s7, s87, 0
	s_add_u32 s8, s86, 0x1100
	s_addc_u32 s9, s87, 0
	s_add_u32 s10, s86, 0x1200
	s_addc_u32 s11, s87, 0
	s_waitcnt lgkmcnt(0)
	s_mul_i32 s0, s12, s0
	s_add_u32 s12, s86, 0x1300
	s_mul_i32 s0, s0, s13
	s_addc_u32 s13, s87, 0
	s_mov_b32 s1, 1
	v_mov_b32_e32 v16, 0
	s_branch .LBB0_2104
